# HGRN2 norm step: b_out_g scales staged once per item in LDS (512 B behind sTot) instead of 8 global loads per chunk waited behind each store
# baseline (speedup 1.0000x reference)
.LBB0_173:
	s_or_b64 exec, exec, s[42:43]
	s_waitcnt lgkmcnt(0)
	s_barrier
	ds_read_b32 v2, v126
	s_mov_b64 s[42:43], -1
	s_waitcnt lgkmcnt(0)
	v_cmp_lt_i32_e32 vcc, 31, v2
	v_readfirstlane_b32 s45, v2
	s_cbranch_vccnz .LBB0_168
	s_setprio 3
	v_and_b32_e32 v236, 3, v147
	v_lshlrev_b32_e32 v236, 7, v236
	v_add_u32_e32 v236, 0x11e00, v236
	global_load_dwordx4 v[240:243], v[128:129], off
	global_load_dwordx4 v[244:247], v[128:129], off offset:16
	global_load_dwordx4 v[248:251], v[128:129], off offset:32
	s_waitcnt vmcnt(0)
	ds_write_b128 v236, v[240:243]
	ds_write_b128 v236, v[244:247] offset:16
	ds_write_b128 v236, v[248:251] offset:32
	s_waitcnt lgkmcnt(0)
	global_load_dwordx4 v[240:243], v[128:129], off offset:48
	global_load_dwordx4 v[244:247], v[128:129], off offset:64
	global_load_dwordx4 v[248:251], v[128:129], off offset:80
	s_waitcnt vmcnt(0)
	ds_write_b128 v236, v[240:243] offset:48
	ds_write_b128 v236, v[244:247] offset:64
	ds_write_b128 v236, v[248:251] offset:80
	s_waitcnt lgkmcnt(0)
	global_load_dwordx4 v[240:243], v[128:129], off offset:96
	global_load_dwordx4 v[244:247], v[128:129], off offset:112
	s_waitcnt vmcnt(0)
	ds_write_b128 v236, v[240:243] offset:96
	ds_write_b128 v236, v[244:247] offset:112
	s_waitcnt lgkmcnt(0)
	v_readfirstlane_b32 s44, v147
	s_lshr_b32 s44, s44, 1
	s_ashr_i32 s42, s45, 2
	s_and_b32 s44, s44, 0x7fffffe0
	s_ashr_i32 s43, s42, 31
	v_or_b32_e32 v2, s44, v149
	v_cmp_lt_i32_e32 vcc, v166, v167
	s_and_b32 s45, s45, 3
	v_mul_lo_u32 v2, v2, s3
	v_cndmask_b32_e32 v3, v165, v166, vcc
	v_cmp_lt_i32_e32 vcc, v168, v167
	s_lshl_b64 s[46:47], s[42:43], 22
	s_lshl_b32 s51, s45, 8
	s_lshl_b64 s[42:43], s[42:43], 23
	s_lshl_b32 s45, s45, 9
	v_or_b32_e32 v170, v153, v2
	v_mov_b32_e32 v2, 0
	v_lshlrev_b32_e32 v172, 2, v3
	v_cndmask_b32_e32 v3, v165, v168, vcc
	s_or_b32 s46, s46, s51
	s_or_b32 s76, s42, s45
	s_mov_b32 s77, s43
	s_or_b32 s42, s42, s51
	v_lshl_add_u32 v171, s44, 2, v156
	s_mov_b32 s44, 64
	v_lshlrev_b32_e32 v173, 2, v3
	v_lshl_add_u64 v[138:139], s[46:47], 0, v[130:131]
	v_lshl_add_u64 v[140:141], s[76:77], 0, v[132:133]
	v_lshl_add_u64 v[142:143], s[46:47], 0, v[134:135]
	v_lshl_add_u64 v[144:145], s[42:43], 0, v[136:137]
	v_add_u32_e32 v174, v170, v153
	v_mov_b32_e32 v3, v2
	v_mov_b32_e32 v4, v2
	v_mov_b32_e32 v5, v2
	v_mov_b32_e32 v6, v2
	v_mov_b32_e32 v7, v2
	v_mov_b32_e32 v8, v2
	v_mov_b32_e32 v9, v2
	v_mov_b32_e32 v10, v2
	v_mov_b32_e32 v11, v2
	v_mov_b32_e32 v12, v2
	v_mov_b32_e32 v13, v2
	v_mov_b32_e32 v14, v2
	v_mov_b32_e32 v15, v2
	v_mov_b32_e32 v16, v2
	v_mov_b32_e32 v17, v2
	v_mov_b32_e32 v18, v2
	v_mov_b32_e32 v19, v2
	v_mov_b32_e32 v20, v2
	v_mov_b32_e32 v21, v2
	v_mov_b32_e32 v22, v2
	v_mov_b32_e32 v23, v2
	v_mov_b32_e32 v24, v2
	v_mov_b32_e32 v25, v2
	v_mov_b32_e32 v26, v2
	v_mov_b32_e32 v27, v2
	v_mov_b32_e32 v28, v2
	v_mov_b32_e32 v29, v2
	v_mov_b32_e32 v30, v2
	v_mov_b32_e32 v31, v2
	v_mov_b32_e32 v32, v2
	v_mov_b32_e32 v33, v2
	v_mov_b32_e32 v34, v2
	v_mov_b32_e32 v35, v2
	v_mov_b32_e32 v36, v2
	v_mov_b32_e32 v37, v2
	v_mov_b32_e32 v38, v2
	v_mov_b32_e32 v39, v2
	v_mov_b32_e32 v40, v2
	v_mov_b32_e32 v41, v2
	v_mov_b32_e32 v42, v2
	v_mov_b32_e32 v43, v2
	v_mov_b32_e32 v44, v2
	v_mov_b32_e32 v45, v2
	v_mov_b32_e32 v46, v2
	v_mov_b32_e32 v47, v2
	v_mov_b32_e32 v48, v2
	v_mov_b32_e32 v49, v2
	v_mov_b32_e32 v50, v2
	v_mov_b32_e32 v51, v2
	v_mov_b32_e32 v52, v2
	v_mov_b32_e32 v53, v2
	v_mov_b32_e32 v54, v2
	v_mov_b32_e32 v55, v2
	v_mov_b32_e32 v56, v2
	v_mov_b32_e32 v57, v2
	v_mov_b32_e32 v58, v2
	v_mov_b32_e32 v59, v2
	v_mov_b32_e32 v60, v2
	v_mov_b32_e32 v61, v2
	v_mov_b32_e32 v62, v2
	v_mov_b32_e32 v63, v2
	v_mov_b32_e32 v64, v2
	v_mov_b32_e32 v65, v2
	s_branch .LBB0_176
.LBB0_175:
	s_or_b64 exec, exec, s[42:43]
	s_waitcnt lgkmcnt(0)
	v_cndmask_b32_e64 v195, v195, 0, s[4:5]
	v_add_f32_e32 v195, v96, v195
	v_max_f32_e32 v196, 0xc2a00000, v195
	v_mul_f32_e32 v197, 0x3fb8aa3b, v196
	v_mul_f32_e32 v96, 0x3fb8aa3b, v96
	v_exp_f32_e32 v197, v197
	v_exp_f32_e32 v96, v96
	v_mul_f32_e32 v196, 0xbfb8aa3b, v196
	v_exp_f32_e32 v196, v196
	v_lshlrev_b32_e32 v194, 16, v194
	v_sub_f32_e32 v96, 1.0, v96
	v_mul_f32_e32 v194, v197, v194
	v_mul_f32_e32 v96, v96, v196
	v_bfe_u32 v196, v194, 16, 1
	v_add3_u32 v194, v194, v196, s33
	ds_write_b16_d16_hi v152, v194
	v_bfe_u32 v194, v96, 16, 1
	v_add3_u32 v96, v96, v194, s33
	v_lshrrev_b32_e32 v96, 16, v96
	ds_write_b16 v152, v96 offset:17408
	ds_write_b16 v161, v96 offset:34816
	v_add_f32_e32 v96, v97, v195
	v_max_f32_e32 v194, 0xc2a00000, v96
	v_mul_f32_e32 v195, 0x3fb8aa3b, v194
	v_mul_f32_e32 v97, 0x3fb8aa3b, v97
	v_exp_f32_e32 v195, v195
	v_exp_f32_e32 v97, v97
	v_mul_f32_e32 v194, 0xbfb8aa3b, v194
	v_exp_f32_e32 v194, v194
	v_lshlrev_b32_e32 v193, 16, v193
	v_sub_f32_e32 v97, 1.0, v97
	v_mul_f32_e32 v193, v195, v193
	v_mul_f32_e32 v97, v97, v194
	v_bfe_u32 v194, v193, 16, 1
	v_add3_u32 v193, v193, v194, s33
	ds_write_b16_d16_hi v152, v193 offset:272
	v_bfe_u32 v193, v97, 16, 1
	v_add3_u32 v97, v97, v193, s33
	v_lshrrev_b32_e32 v97, 16, v97
	v_add_f32_e32 v96, v94, v96
	ds_write_b16 v152, v97 offset:17680
	ds_write_b16 v161, v97 offset:34818
	v_max_f32_e32 v97, 0xc2a00000, v96
	v_mul_f32_e32 v193, 0x3fb8aa3b, v97
	v_mul_f32_e32 v94, 0x3fb8aa3b, v94
	v_exp_f32_e32 v193, v193
	v_exp_f32_e32 v94, v94
	v_mul_f32_e32 v97, 0xbfb8aa3b, v97
	v_exp_f32_e32 v97, v97
	v_lshlrev_b32_e32 v192, 16, v192
	v_sub_f32_e32 v94, 1.0, v94
	v_mul_f32_e32 v192, v193, v192
	v_mul_f32_e32 v94, v94, v97
	v_bfe_u32 v97, v192, 16, 1
	v_add3_u32 v97, v192, v97, s33
	ds_write_b16_d16_hi v152, v97 offset:544
	v_bfe_u32 v97, v94, 16, 1
	v_add3_u32 v94, v94, v97, s33
	v_lshrrev_b32_e32 v94, 16, v94
	ds_write_b16 v152, v94 offset:17952
	ds_write_b16 v161, v94 offset:34820
	v_add_f32_e32 v94, v95, v96
	v_max_f32_e32 v96, 0xc2a00000, v94
	v_mul_f32_e32 v97, 0x3fb8aa3b, v96
	v_mul_f32_e32 v95, 0x3fb8aa3b, v95
	v_exp_f32_e32 v97, v97
	v_exp_f32_e32 v95, v95
	v_mul_f32_e32 v96, 0xbfb8aa3b, v96
	v_exp_f32_e32 v96, v96
	v_lshlrev_b32_e32 v191, 16, v191
	v_sub_f32_e32 v95, 1.0, v95
	v_mul_f32_e32 v97, v97, v191
	v_mul_f32_e32 v95, v95, v96
	v_bfe_u32 v96, v97, 16, 1
	v_add3_u32 v96, v97, v96, s33
	ds_write_b16_d16_hi v152, v96 offset:816
	v_bfe_u32 v96, v95, 16, 1
	v_add3_u32 v95, v95, v96, s33
	v_lshrrev_b32_e32 v95, 16, v95
	v_add_f32_e32 v94, v92, v94
	ds_write_b16 v152, v95 offset:18224
	ds_write_b16 v161, v95 offset:34822
	v_max_f32_e32 v95, 0xc2a00000, v94
	v_mul_f32_e32 v96, 0x3fb8aa3b, v95
	v_mul_f32_e32 v92, 0x3fb8aa3b, v92
	v_exp_f32_e32 v96, v96
	v_exp_f32_e32 v92, v92
	v_mul_f32_e32 v95, 0xbfb8aa3b, v95
	v_exp_f32_e32 v95, v95
	v_lshlrev_b32_e32 v97, 16, v190
	v_sub_f32_e32 v92, 1.0, v92
	v_mul_f32_e32 v96, v96, v97
	v_mul_f32_e32 v92, v92, v95
	v_bfe_u32 v95, v96, 16, 1
	v_add3_u32 v95, v96, v95, s33
	ds_write_b16_d16_hi v152, v95 offset:1088
	v_bfe_u32 v95, v92, 16, 1
	v_add3_u32 v92, v92, v95, s33
	v_lshrrev_b32_e32 v92, 16, v92
	ds_write_b16 v152, v92 offset:18496
	ds_write_b16 v161, v92 offset:34824
	v_add_f32_e32 v92, v93, v94
	v_max_f32_e32 v94, 0xc2a00000, v92
	v_mul_f32_e32 v95, 0x3fb8aa3b, v94
	v_mul_f32_e32 v93, 0x3fb8aa3b, v93
	v_exp_f32_e32 v95, v95
	v_exp_f32_e32 v93, v93
	v_mul_f32_e32 v94, 0xbfb8aa3b, v94
	v_exp_f32_e32 v94, v94
	v_lshlrev_b32_e32 v96, 16, v189
	v_sub_f32_e32 v93, 1.0, v93
	v_mul_f32_e32 v95, v95, v96
	v_mul_f32_e32 v93, v93, v94
	v_bfe_u32 v94, v95, 16, 1
	v_add3_u32 v94, v95, v94, s33
	ds_write_b16_d16_hi v152, v94 offset:1360
	v_bfe_u32 v94, v93, 16, 1
	v_add3_u32 v93, v93, v94, s33
	v_lshrrev_b32_e32 v93, 16, v93
	v_add_f32_e32 v92, v90, v92
	ds_write_b16 v152, v93 offset:18768
	ds_write_b16 v161, v93 offset:34826
	v_max_f32_e32 v93, 0xc2a00000, v92
	v_mul_f32_e32 v94, 0x3fb8aa3b, v93
	v_mul_f32_e32 v90, 0x3fb8aa3b, v90
	v_exp_f32_e32 v94, v94
	v_exp_f32_e32 v90, v90
	v_mul_f32_e32 v93, 0xbfb8aa3b, v93
	v_exp_f32_e32 v93, v93
	v_lshlrev_b32_e32 v95, 16, v188
	v_sub_f32_e32 v90, 1.0, v90
	v_mul_f32_e32 v94, v94, v95
	v_mul_f32_e32 v90, v90, v93
	v_bfe_u32 v93, v94, 16, 1
	v_add3_u32 v93, v94, v93, s33
	ds_write_b16_d16_hi v152, v93 offset:1632
	v_bfe_u32 v93, v90, 16, 1
	v_add3_u32 v90, v90, v93, s33
	v_lshrrev_b32_e32 v90, 16, v90
	ds_write_b16 v152, v90 offset:19040
	ds_write_b16 v161, v90 offset:34828
	v_add_f32_e32 v90, v91, v92
	v_max_f32_e32 v92, 0xc2a00000, v90
	v_mul_f32_e32 v93, 0x3fb8aa3b, v92
	v_mul_f32_e32 v91, 0x3fb8aa3b, v91
	v_exp_f32_e32 v93, v93
	v_exp_f32_e32 v91, v91
	v_mul_f32_e32 v92, 0xbfb8aa3b, v92
	v_exp_f32_e32 v92, v92
	v_lshlrev_b32_e32 v94, 16, v186
	v_sub_f32_e32 v91, 1.0, v91
	v_mul_f32_e32 v93, v93, v94
	v_mul_f32_e32 v91, v91, v92
	v_bfe_u32 v92, v93, 16, 1
	v_add3_u32 v92, v93, v92, s33
	ds_write_b16_d16_hi v152, v92 offset:1904
	v_bfe_u32 v92, v91, 16, 1
	v_add3_u32 v91, v91, v92, s33
	v_lshrrev_b32_e32 v91, 16, v91
	v_add_f32_e32 v90, v88, v90
	ds_write_b16 v152, v91 offset:19312
	ds_write_b16 v161, v91 offset:34830
	v_max_f32_e32 v91, 0xc2a00000, v90
	v_mul_f32_e32 v92, 0x3fb8aa3b, v91
	v_mul_f32_e32 v88, 0x3fb8aa3b, v88
	v_exp_f32_e32 v92, v92
	v_exp_f32_e32 v88, v88
	v_mul_f32_e32 v91, 0xbfb8aa3b, v91
	v_exp_f32_e32 v91, v91
	v_lshlrev_b32_e32 v93, 16, v187
	v_sub_f32_e32 v88, 1.0, v88
	v_mul_f32_e32 v92, v92, v93
	v_mul_f32_e32 v88, v88, v91
	v_bfe_u32 v91, v92, 16, 1
	v_add3_u32 v91, v92, v91, s33
	ds_write_b16_d16_hi v152, v91 offset:2176
	v_bfe_u32 v91, v88, 16, 1
	v_add3_u32 v88, v88, v91, s33
	v_lshrrev_b32_e32 v88, 16, v88
	ds_write_b16 v152, v88 offset:19584
	ds_write_b16 v161, v88 offset:34832
	v_add_f32_e32 v88, v89, v90
	v_max_f32_e32 v90, 0xc2a00000, v88
	v_mul_f32_e32 v91, 0x3fb8aa3b, v90
	v_mul_f32_e32 v89, 0x3fb8aa3b, v89
	v_exp_f32_e32 v91, v91
	v_exp_f32_e32 v89, v89
	v_mul_f32_e32 v90, 0xbfb8aa3b, v90
	v_exp_f32_e32 v90, v90
	v_lshlrev_b32_e32 v92, 16, v185
	v_sub_f32_e32 v89, 1.0, v89
	v_mul_f32_e32 v91, v91, v92
	v_mul_f32_e32 v89, v89, v90
	v_bfe_u32 v90, v91, 16, 1
	v_add3_u32 v90, v91, v90, s33
	ds_write_b16_d16_hi v152, v90 offset:2448
	v_bfe_u32 v90, v89, 16, 1
	v_add3_u32 v89, v89, v90, s33
	v_lshrrev_b32_e32 v89, 16, v89
	v_add_f32_e32 v88, v86, v88
	ds_write_b16 v152, v89 offset:19856
	ds_write_b16 v161, v89 offset:34834
	v_max_f32_e32 v89, 0xc2a00000, v88
	v_mul_f32_e32 v90, 0x3fb8aa3b, v89
	v_mul_f32_e32 v86, 0x3fb8aa3b, v86
	v_exp_f32_e32 v90, v90
	v_exp_f32_e32 v86, v86
	v_mul_f32_e32 v89, 0xbfb8aa3b, v89
	v_exp_f32_e32 v89, v89
	v_lshlrev_b32_e32 v91, 16, v184
	v_sub_f32_e32 v86, 1.0, v86
	v_mul_f32_e32 v90, v90, v91
	v_mul_f32_e32 v86, v86, v89
	v_bfe_u32 v89, v90, 16, 1
	v_add3_u32 v89, v90, v89, s33
	ds_write_b16_d16_hi v152, v89 offset:2720
	v_bfe_u32 v89, v86, 16, 1
	v_add3_u32 v86, v86, v89, s33
	v_lshrrev_b32_e32 v86, 16, v86
	ds_write_b16 v152, v86 offset:20128
	ds_write_b16 v161, v86 offset:34836
	v_add_f32_e32 v86, v87, v88
	v_max_f32_e32 v88, 0xc2a00000, v86
	v_mul_f32_e32 v89, 0x3fb8aa3b, v88
	v_mul_f32_e32 v87, 0x3fb8aa3b, v87
	v_exp_f32_e32 v89, v89
	v_exp_f32_e32 v87, v87
	v_mul_f32_e32 v88, 0xbfb8aa3b, v88
	v_exp_f32_e32 v88, v88
	v_lshlrev_b32_e32 v90, 16, v183
	v_sub_f32_e32 v87, 1.0, v87
	v_mul_f32_e32 v89, v89, v90
	v_mul_f32_e32 v87, v87, v88
	v_bfe_u32 v88, v89, 16, 1
	v_add3_u32 v88, v89, v88, s33
	ds_write_b16_d16_hi v152, v88 offset:2992
	v_bfe_u32 v88, v87, 16, 1
	v_add3_u32 v87, v87, v88, s33
	v_lshrrev_b32_e32 v87, 16, v87
	v_add_f32_e32 v86, v84, v86
	ds_write_b16 v152, v87 offset:20400
	ds_write_b16 v161, v87 offset:34838
	v_max_f32_e32 v87, 0xc2a00000, v86
	v_mul_f32_e32 v88, 0x3fb8aa3b, v87
	v_mul_f32_e32 v84, 0x3fb8aa3b, v84
	v_exp_f32_e32 v88, v88
	v_exp_f32_e32 v84, v84
	v_mul_f32_e32 v87, 0xbfb8aa3b, v87
	v_exp_f32_e32 v87, v87
	v_lshlrev_b32_e32 v89, 16, v182
	v_sub_f32_e32 v84, 1.0, v84
	v_mul_f32_e32 v88, v88, v89
	v_mul_f32_e32 v84, v84, v87
	v_bfe_u32 v87, v88, 16, 1
	v_add3_u32 v87, v88, v87, s33
	ds_write_b16_d16_hi v152, v87 offset:3264
	v_bfe_u32 v87, v84, 16, 1
	v_add3_u32 v84, v84, v87, s33
	v_lshrrev_b32_e32 v84, 16, v84
	ds_write_b16 v152, v84 offset:20672
	ds_write_b16 v161, v84 offset:34840
	v_add_f32_e32 v84, v85, v86
	v_max_f32_e32 v86, 0xc2a00000, v84
	v_mul_f32_e32 v87, 0x3fb8aa3b, v86
	v_mul_f32_e32 v85, 0x3fb8aa3b, v85
	v_exp_f32_e32 v87, v87
	v_exp_f32_e32 v85, v85
	v_mul_f32_e32 v86, 0xbfb8aa3b, v86
	v_exp_f32_e32 v86, v86
	v_lshlrev_b32_e32 v88, 16, v181
	v_sub_f32_e32 v85, 1.0, v85
	v_mul_f32_e32 v87, v87, v88
	v_mul_f32_e32 v85, v85, v86
	v_bfe_u32 v86, v87, 16, 1
	v_add3_u32 v86, v87, v86, s33
	ds_write_b16_d16_hi v152, v86 offset:3536
	v_bfe_u32 v86, v85, 16, 1
	v_add3_u32 v85, v85, v86, s33
	v_lshrrev_b32_e32 v85, 16, v85
	v_add_f32_e32 v84, v82, v84
	ds_write_b16 v152, v85 offset:20944
	ds_write_b16 v161, v85 offset:34842
	v_max_f32_e32 v85, 0xc2a00000, v84
	v_mul_f32_e32 v86, 0x3fb8aa3b, v85
	v_mul_f32_e32 v82, 0x3fb8aa3b, v82
	v_exp_f32_e32 v86, v86
	v_exp_f32_e32 v82, v82
	v_mul_f32_e32 v85, 0xbfb8aa3b, v85
	v_exp_f32_e32 v85, v85
	v_lshlrev_b32_e32 v87, 16, v180
	v_sub_f32_e32 v82, 1.0, v82
	v_mul_f32_e32 v86, v86, v87
	v_mul_f32_e32 v82, v82, v85
	v_bfe_u32 v85, v86, 16, 1
	v_add3_u32 v85, v86, v85, s33
	ds_write_b16_d16_hi v152, v85 offset:3808
	v_bfe_u32 v85, v82, 16, 1
	v_add3_u32 v82, v82, v85, s33
	v_lshrrev_b32_e32 v82, 16, v82
	ds_write_b16 v152, v82 offset:21216
	ds_write_b16 v161, v82 offset:34844
	v_add_f32_e32 v82, v83, v84
	v_max_f32_e32 v84, 0xc2a00000, v82
	v_mul_f32_e32 v85, 0x3fb8aa3b, v84
	v_mul_f32_e32 v83, 0x3fb8aa3b, v83
	v_exp_f32_e32 v85, v85
	v_exp_f32_e32 v83, v83
	v_mul_f32_e32 v84, 0xbfb8aa3b, v84
	v_exp_f32_e32 v84, v84
	v_lshlrev_b32_e32 v86, 16, v178
	v_sub_f32_e32 v83, 1.0, v83
	v_mul_f32_e32 v85, v85, v86
	v_mul_f32_e32 v83, v83, v84
	v_bfe_u32 v84, v85, 16, 1
	v_add3_u32 v84, v85, v84, s33
	ds_write_b16_d16_hi v152, v84 offset:4080
	v_bfe_u32 v84, v83, 16, 1
	v_add3_u32 v83, v83, v84, s33
	v_lshrrev_b32_e32 v83, 16, v83
	v_add_f32_e32 v82, v80, v82
	ds_write_b16 v152, v83 offset:21488
	ds_write_b16 v161, v83 offset:34846
	v_max_f32_e32 v83, 0xc2a00000, v82
	v_mul_f32_e32 v84, 0x3fb8aa3b, v83
	v_mul_f32_e32 v80, 0x3fb8aa3b, v80
	v_exp_f32_e32 v84, v84
	v_exp_f32_e32 v80, v80
	v_mul_f32_e32 v83, 0xbfb8aa3b, v83
	v_exp_f32_e32 v83, v83
	v_lshlrev_b32_e32 v85, 16, v179
	v_sub_f32_e32 v80, 1.0, v80
	v_mul_f32_e32 v84, v84, v85
	v_mul_f32_e32 v80, v80, v83
	v_bfe_u32 v83, v84, 16, 1
	v_add3_u32 v83, v84, v83, s33
	ds_write_b16_d16_hi v152, v83 offset:4352
	v_bfe_u32 v83, v80, 16, 1
	v_add3_u32 v80, v80, v83, s33
	v_lshrrev_b32_e32 v80, 16, v80
	ds_write_b16 v152, v80 offset:21760
	ds_write_b16 v161, v80 offset:34848
	v_add_f32_e32 v80, v81, v82
	v_max_f32_e32 v82, 0xc2a00000, v80
	v_mul_f32_e32 v83, 0x3fb8aa3b, v82
	v_mul_f32_e32 v81, 0x3fb8aa3b, v81
	v_exp_f32_e32 v83, v83
	v_exp_f32_e32 v81, v81
	v_mul_f32_e32 v82, 0xbfb8aa3b, v82
	v_exp_f32_e32 v82, v82
	v_lshlrev_b32_e32 v84, 16, v177
	v_sub_f32_e32 v81, 1.0, v81
	v_mul_f32_e32 v83, v83, v84
	v_mul_f32_e32 v81, v81, v82
	v_bfe_u32 v82, v83, 16, 1
	v_add3_u32 v82, v83, v82, s33
	ds_write_b16_d16_hi v152, v82 offset:4624
	v_bfe_u32 v82, v81, 16, 1
	v_add3_u32 v81, v81, v82, s33
	v_lshrrev_b32_e32 v81, 16, v81
	v_add_f32_e32 v80, v78, v80
	ds_write_b16 v152, v81 offset:22032
	ds_write_b16 v161, v81 offset:34850
	v_max_f32_e32 v81, 0xc2a00000, v80
	v_mul_f32_e32 v82, 0x3fb8aa3b, v81
	v_mul_f32_e32 v78, 0x3fb8aa3b, v78
	v_exp_f32_e32 v82, v82
	v_exp_f32_e32 v78, v78
	v_mul_f32_e32 v81, 0xbfb8aa3b, v81
	v_exp_f32_e32 v81, v81
	v_lshlrev_b32_e32 v83, 16, v176
	v_sub_f32_e32 v78, 1.0, v78
	v_mul_f32_e32 v82, v82, v83
	v_mul_f32_e32 v78, v78, v81
	v_bfe_u32 v81, v82, 16, 1
	v_add3_u32 v81, v82, v81, s33
	ds_write_b16_d16_hi v152, v81 offset:4896
	v_bfe_u32 v81, v78, 16, 1
	v_add3_u32 v78, v78, v81, s33
	v_lshrrev_b32_e32 v78, 16, v78
	ds_write_b16 v152, v78 offset:22304
	ds_write_b16 v161, v78 offset:34852
	v_add_f32_e32 v78, v79, v80
	v_max_f32_e32 v80, 0xc2a00000, v78
	v_mul_f32_e32 v81, 0x3fb8aa3b, v80
	v_mul_f32_e32 v79, 0x3fb8aa3b, v79
	v_exp_f32_e32 v81, v81
	v_exp_f32_e32 v79, v79
	v_mul_f32_e32 v80, 0xbfb8aa3b, v80
	v_exp_f32_e32 v80, v80
	v_lshlrev_b32_e32 v82, 16, v175
	v_sub_f32_e32 v79, 1.0, v79
	v_mul_f32_e32 v81, v81, v82
	v_mul_f32_e32 v79, v79, v80
	v_bfe_u32 v80, v81, 16, 1
	v_add3_u32 v80, v81, v80, s33
	ds_write_b16_d16_hi v152, v80 offset:5168
	v_bfe_u32 v80, v79, 16, 1
	v_add3_u32 v79, v79, v80, s33
	v_lshrrev_b32_e32 v79, 16, v79
	v_add_f32_e32 v78, v76, v78
	ds_write_b16 v152, v79 offset:22576
	ds_write_b16 v161, v79 offset:34854
	v_max_f32_e32 v79, 0xc2a00000, v78
	v_mul_f32_e32 v80, 0x3fb8aa3b, v79
	v_mul_f32_e32 v76, 0x3fb8aa3b, v76
	v_exp_f32_e32 v80, v80
	v_exp_f32_e32 v76, v76
	v_mul_f32_e32 v79, 0xbfb8aa3b, v79
	v_exp_f32_e32 v79, v79
	v_lshlrev_b32_e32 v81, 16, v125
	v_sub_f32_e32 v76, 1.0, v76
	v_mul_f32_e32 v80, v80, v81
	v_mul_f32_e32 v76, v76, v79
	v_bfe_u32 v79, v80, 16, 1
	v_add3_u32 v79, v80, v79, s33
	ds_write_b16_d16_hi v152, v79 offset:5440
	v_bfe_u32 v79, v76, 16, 1
	v_add3_u32 v76, v76, v79, s33
	v_lshrrev_b32_e32 v76, 16, v76
	ds_write_b16 v152, v76 offset:22848
	ds_write_b16 v161, v76 offset:34856
	v_add_f32_e32 v76, v77, v78
	v_max_f32_e32 v78, 0xc2a00000, v76
	v_mul_f32_e32 v79, 0x3fb8aa3b, v78
	v_mul_f32_e32 v77, 0x3fb8aa3b, v77
	v_exp_f32_e32 v79, v79
	v_exp_f32_e32 v77, v77
	v_mul_f32_e32 v78, 0xbfb8aa3b, v78
	v_exp_f32_e32 v78, v78
	v_lshlrev_b32_e32 v80, 16, v124
	v_sub_f32_e32 v77, 1.0, v77
	v_mul_f32_e32 v79, v79, v80
	v_mul_f32_e32 v77, v77, v78
	v_bfe_u32 v78, v79, 16, 1
	v_add3_u32 v78, v79, v78, s33
	ds_write_b16_d16_hi v152, v78 offset:5712
	v_bfe_u32 v78, v77, 16, 1
	v_add3_u32 v77, v77, v78, s33
	v_lshrrev_b32_e32 v77, 16, v77
	v_add_f32_e32 v76, v74, v76
	ds_write_b16 v152, v77 offset:23120
	ds_write_b16 v161, v77 offset:34858
	v_max_f32_e32 v77, 0xc2a00000, v76
	v_mul_f32_e32 v78, 0x3fb8aa3b, v77
	v_mul_f32_e32 v74, 0x3fb8aa3b, v74
	v_exp_f32_e32 v78, v78
	v_exp_f32_e32 v74, v74
	v_mul_f32_e32 v77, 0xbfb8aa3b, v77
	v_exp_f32_e32 v77, v77
	v_lshlrev_b32_e32 v79, 16, v123
	v_sub_f32_e32 v74, 1.0, v74
	v_mul_f32_e32 v78, v78, v79
	v_mul_f32_e32 v74, v74, v77
	v_bfe_u32 v77, v78, 16, 1
	v_add3_u32 v77, v78, v77, s33
	ds_write_b16_d16_hi v152, v77 offset:5984
	v_bfe_u32 v77, v74, 16, 1
	v_add3_u32 v74, v74, v77, s33
	v_lshrrev_b32_e32 v74, 16, v74
	ds_write_b16 v152, v74 offset:23392
	ds_write_b16 v161, v74 offset:34860
	v_add_f32_e32 v74, v75, v76
	v_max_f32_e32 v76, 0xc2a00000, v74
	v_mul_f32_e32 v77, 0x3fb8aa3b, v76
	v_mul_f32_e32 v75, 0x3fb8aa3b, v75
	v_exp_f32_e32 v77, v77
	v_exp_f32_e32 v75, v75
	v_mul_f32_e32 v76, 0xbfb8aa3b, v76
	v_exp_f32_e32 v76, v76
	v_lshlrev_b32_e32 v78, 16, v105
	v_sub_f32_e32 v75, 1.0, v75
	v_mul_f32_e32 v77, v77, v78
	v_mul_f32_e32 v75, v75, v76
	v_bfe_u32 v76, v77, 16, 1
	v_add3_u32 v76, v77, v76, s33
	ds_write_b16_d16_hi v152, v76 offset:6256
	v_bfe_u32 v76, v75, 16, 1
	v_add3_u32 v75, v75, v76, s33
	v_lshrrev_b32_e32 v75, 16, v75
	v_add_f32_e32 v74, v72, v74
	ds_write_b16 v152, v75 offset:23664
	ds_write_b16 v161, v75 offset:34862
	v_max_f32_e32 v75, 0xc2a00000, v74
	v_mul_f32_e32 v76, 0x3fb8aa3b, v75
	v_mul_f32_e32 v72, 0x3fb8aa3b, v72
	v_exp_f32_e32 v76, v76
	v_exp_f32_e32 v72, v72
	v_mul_f32_e32 v75, 0xbfb8aa3b, v75
	v_exp_f32_e32 v75, v75
	v_lshlrev_b32_e32 v77, 16, v122
	v_sub_f32_e32 v72, 1.0, v72
	v_mul_f32_e32 v76, v76, v77
	v_mul_f32_e32 v72, v72, v75
	v_bfe_u32 v75, v76, 16, 1
	v_add3_u32 v75, v76, v75, s33
	ds_write_b16_d16_hi v152, v75 offset:6528
	v_bfe_u32 v75, v72, 16, 1
	v_add3_u32 v72, v72, v75, s33
	v_lshrrev_b32_e32 v72, 16, v72
	ds_write_b16 v152, v72 offset:23936
	ds_write_b16 v161, v72 offset:34864
	v_add_f32_e32 v72, v73, v74
	v_max_f32_e32 v74, 0xc2a00000, v72
	v_mul_f32_e32 v75, 0x3fb8aa3b, v74
	v_mul_f32_e32 v73, 0x3fb8aa3b, v73
	v_exp_f32_e32 v75, v75
	v_exp_f32_e32 v73, v73
	v_mul_f32_e32 v74, 0xbfb8aa3b, v74
	v_exp_f32_e32 v74, v74
	v_lshlrev_b32_e32 v76, 16, v104
	v_sub_f32_e32 v73, 1.0, v73
	v_mul_f32_e32 v75, v75, v76
	v_mul_f32_e32 v73, v73, v74
	v_bfe_u32 v74, v75, 16, 1
	v_add3_u32 v74, v75, v74, s33
	ds_write_b16_d16_hi v152, v74 offset:6800
	v_bfe_u32 v74, v73, 16, 1
	v_add3_u32 v73, v73, v74, s33
	v_lshrrev_b32_e32 v73, 16, v73
	v_add_f32_e32 v72, v70, v72
	ds_write_b16 v152, v73 offset:24208
	ds_write_b16 v161, v73 offset:34866
	v_max_f32_e32 v73, 0xc2a00000, v72
	v_mul_f32_e32 v74, 0x3fb8aa3b, v73
	v_mul_f32_e32 v70, 0x3fb8aa3b, v70
	v_exp_f32_e32 v74, v74
	v_exp_f32_e32 v70, v70
	v_mul_f32_e32 v73, 0xbfb8aa3b, v73
	v_exp_f32_e32 v73, v73
	v_lshlrev_b32_e32 v75, 16, v103
	v_sub_f32_e32 v70, 1.0, v70
	v_mul_f32_e32 v74, v74, v75
	v_mul_f32_e32 v70, v70, v73
	v_bfe_u32 v73, v74, 16, 1
	v_add3_u32 v73, v74, v73, s33
	ds_write_b16_d16_hi v152, v73 offset:7072
	v_bfe_u32 v73, v70, 16, 1
	v_add3_u32 v70, v70, v73, s33
	v_lshrrev_b32_e32 v70, 16, v70
	ds_write_b16 v152, v70 offset:24480
	ds_write_b16 v161, v70 offset:34868
	v_add_f32_e32 v70, v71, v72
	v_max_f32_e32 v72, 0xc2a00000, v70
	v_mul_f32_e32 v73, 0x3fb8aa3b, v72
	v_mul_f32_e32 v71, 0x3fb8aa3b, v71
	v_exp_f32_e32 v73, v73
	v_exp_f32_e32 v71, v71
	v_mul_f32_e32 v72, 0xbfb8aa3b, v72
	v_exp_f32_e32 v72, v72
	v_lshlrev_b32_e32 v74, 16, v102
	v_sub_f32_e32 v71, 1.0, v71
	v_mul_f32_e32 v73, v73, v74
	v_mul_f32_e32 v71, v71, v72
	v_bfe_u32 v72, v73, 16, 1
	v_add3_u32 v72, v73, v72, s33
	ds_write_b16_d16_hi v152, v72 offset:7344
	v_bfe_u32 v72, v71, 16, 1
	v_add3_u32 v71, v71, v72, s33
	v_lshrrev_b32_e32 v71, 16, v71
	v_add_f32_e32 v70, v68, v70
	ds_write_b16 v152, v71 offset:24752
	ds_write_b16 v161, v71 offset:34870
	v_max_f32_e32 v71, 0xc2a00000, v70
	v_mul_f32_e32 v72, 0x3fb8aa3b, v71
	v_mul_f32_e32 v68, 0x3fb8aa3b, v68
	v_exp_f32_e32 v72, v72
	v_exp_f32_e32 v68, v68
	v_mul_f32_e32 v71, 0xbfb8aa3b, v71
	v_exp_f32_e32 v71, v71
	v_lshlrev_b32_e32 v73, 16, v101
	v_sub_f32_e32 v68, 1.0, v68
	v_mul_f32_e32 v72, v72, v73
	v_mul_f32_e32 v68, v68, v71
	v_bfe_u32 v71, v72, 16, 1
	v_add3_u32 v71, v72, v71, s33
	ds_write_b16_d16_hi v152, v71 offset:7616
	v_bfe_u32 v71, v68, 16, 1
	v_add3_u32 v68, v68, v71, s33
	v_lshrrev_b32_e32 v68, 16, v68
	ds_write_b16 v152, v68 offset:25024
	ds_write_b16 v161, v68 offset:34872
	v_add_f32_e32 v68, v69, v70
	v_max_f32_e32 v70, 0xc2a00000, v68
	v_mul_f32_e32 v71, 0x3fb8aa3b, v70
	v_mul_f32_e32 v69, 0x3fb8aa3b, v69
	v_exp_f32_e32 v71, v71
	v_exp_f32_e32 v69, v69
	v_mul_f32_e32 v70, 0xbfb8aa3b, v70
	v_exp_f32_e32 v70, v70
	v_lshlrev_b32_e32 v72, 16, v100
	v_sub_f32_e32 v69, 1.0, v69
	v_mul_f32_e32 v71, v71, v72
	v_mul_f32_e32 v69, v69, v70
	v_bfe_u32 v70, v71, 16, 1
	v_add3_u32 v70, v71, v70, s33
	ds_write_b16_d16_hi v152, v70 offset:7888
	v_bfe_u32 v70, v69, 16, 1
	v_add3_u32 v69, v69, v70, s33
	v_lshrrev_b32_e32 v69, 16, v69
	v_add_f32_e32 v68, v66, v68
	ds_write_b16 v152, v69 offset:25296
	ds_write_b16 v161, v69 offset:34874
	v_max_f32_e32 v69, 0xc2a00000, v68
	v_mul_f32_e32 v70, 0x3fb8aa3b, v69
	v_mul_f32_e32 v66, 0x3fb8aa3b, v66
	v_exp_f32_e32 v70, v70
	v_exp_f32_e32 v66, v66
	v_mul_f32_e32 v69, 0xbfb8aa3b, v69
	v_exp_f32_e32 v69, v69
	v_lshlrev_b32_e32 v71, 16, v99
	v_sub_f32_e32 v66, 1.0, v66
	v_mul_f32_e32 v70, v70, v71
	v_mul_f32_e32 v66, v66, v69
	v_bfe_u32 v69, v70, 16, 1
	v_add3_u32 v69, v70, v69, s33
	ds_write_b16_d16_hi v152, v69 offset:8160
	v_bfe_u32 v69, v66, 16, 1
	v_add3_u32 v66, v66, v69, s33
	v_lshrrev_b32_e32 v66, 16, v66
	ds_write_b16 v152, v66 offset:25568
	ds_write_b16 v161, v66 offset:34876
	v_add_f32_e32 v66, v67, v68
	v_max_f32_e32 v66, 0xc2a00000, v66
	v_mul_f32_e32 v68, 0x3fb8aa3b, v66
	v_mul_f32_e32 v67, 0x3fb8aa3b, v67
	v_exp_f32_e32 v68, v68
	v_exp_f32_e32 v67, v67
	v_mul_f32_e32 v66, 0xbfb8aa3b, v66
	v_exp_f32_e32 v66, v66
	v_lshlrev_b32_e32 v69, 16, v98
	v_sub_f32_e32 v67, 1.0, v67
	v_mul_f32_e32 v68, v68, v69
	v_mul_f32_e32 v66, v67, v66
	v_bfe_u32 v67, v68, 16, 1
	v_add3_u32 v67, v68, v67, s33
	ds_write_b16_d16_hi v152, v67 offset:8432
	v_bfe_u32 v67, v66, 16, 1
	v_add3_u32 v66, v66, v67, s33
	v_lshrrev_b32_e32 v66, 16, v66
	ds_write_b16 v152, v66 offset:25840
	ds_write_b16 v161, v66 offset:34878
	s_waitcnt lgkmcnt(0)
	s_barrier
	ds_read_b128 v[98:101], v154 offset:17408
	ds_read_b128 v[82:85], v154 offset:26112
	ds_read_b128 v[102:105], v154 offset:8704
	ds_read_b128 v[66:69], v154
	ds_read_b128 v[122:125], v154 offset:32
	ds_read_b128 v[176:179], v154 offset:17440
	ds_read_b128 v[180:183], v154 offset:26144
	ds_read_b128 v[184:187], v154 offset:8736
	s_waitcnt lgkmcnt(5)
	v_mfma_f32_32x32x16_bf16 v[82:97], v[82:85], v[102:105], 0
	s_waitcnt lgkmcnt(4)
	v_mfma_f32_32x32x16_bf16 v[66:81], v[98:101], v[66:69], 0
	s_waitcnt lgkmcnt(0)
	v_mfma_f32_32x32x16_bf16 v[82:97], v[180:183], v[184:187], v[82:97]
	v_mfma_f32_32x32x16_bf16 v[66:81], v[176:179], v[122:125], v[66:81]
	ds_read_b128 v[122:125], v154 offset:17472
	ds_read_b128 v[180:183], v154 offset:26176
	ds_read_b128 v[188:191], v154 offset:64
	ds_read_b128 v[192:195], v154 offset:8768
	s_waitcnt lgkmcnt(0)
	v_mfma_f32_32x32x16_bf16 v[82:97], v[180:183], v[192:195], v[82:97]
	v_mfma_f32_32x32x16_bf16 v[66:81], v[122:125], v[188:191], v[66:81]
	ds_read_b128 v[180:183], v154 offset:17504
	ds_read_b128 v[188:191], v154 offset:26208
	ds_read_b128 v[196:199], v154 offset:96
	ds_read_b128 v[200:203], v154 offset:8800
	s_waitcnt lgkmcnt(0)
	v_mfma_f32_32x32x16_bf16 v[82:97], v[188:191], v[200:203], v[82:97]
	v_mfma_f32_32x32x16_bf16 v[66:81], v[180:183], v[196:199], v[66:81]
	ds_read_b128 v[188:191], v154 offset:17536
	ds_read_b128 v[196:199], v154 offset:26240
	ds_read_b128 v[204:207], v154 offset:128
	ds_read_b128 v[208:211], v154 offset:8832
	s_waitcnt lgkmcnt(0)
	v_mfma_f32_32x32x16_bf16 v[82:97], v[196:199], v[208:211], v[82:97]
	v_mfma_f32_32x32x16_bf16 v[66:81], v[188:191], v[204:207], v[66:81]
	ds_read_b128 v[196:199], v154 offset:17568
	ds_read_b128 v[204:207], v154 offset:26272
	ds_read_b128 v[212:215], v154 offset:160
	ds_read_b128 v[216:219], v154 offset:8864
	s_waitcnt lgkmcnt(0)
	v_mfma_f32_32x32x16_bf16 v[82:97], v[204:207], v[216:219], v[82:97]
	v_mfma_f32_32x32x16_bf16 v[66:81], v[196:199], v[212:215], v[66:81]
	ds_read_b128 v[204:207], v154 offset:17600
	ds_read_b128 v[212:215], v154 offset:26304
	ds_read_b128 v[220:223], v154 offset:192
	ds_read_b128 v[224:227], v154 offset:8896
	s_waitcnt lgkmcnt(0)
	v_mfma_f32_32x32x16_bf16 v[82:97], v[212:215], v[224:227], v[82:97]
	v_mfma_f32_32x32x16_bf16 v[66:81], v[204:207], v[220:223], v[66:81]
	ds_read_b128 v[212:215], v154 offset:17632
	ds_read_b128 v[220:223], v154 offset:26336
	ds_read_b128 v[228:231], v154 offset:224
	ds_read_b128 v[232:235], v154 offset:8928
	s_waitcnt lgkmcnt(0)
	v_mfma_f32_32x32x16_bf16 v[82:97], v[220:223], v[232:235], v[82:97]
	v_mfma_f32_32x32x16_bf16 v[66:81], v[212:215], v[228:231], v[66:81]
	s_nop 10
	v_cndmask_b32_e64 v175, v96, 0, s[38:39]
	v_cndmask_b32_e64 v220, v97, 0, s[6:7]
	v_cndmask_b32_e64 v221, v94, 0, s[34:35]
	v_cndmask_b32_e64 v222, v95, 0, s[36:37]
	v_cndmask_b32_e64 v223, v92, 0, s[26:27]
	v_cndmask_b32_e64 v228, v93, 0, s[28:29]
	v_cndmask_b32_e64 v229, v90, 0, s[22:23]
	v_cndmask_b32_e64 v230, v91, 0, s[24:25]
	v_mfma_f32_32x32x16_bf16 v[90:105], v[98:101], v[102:105], 0
	v_cndmask_b32_e64 v88, v88, 0, s[18:19]
	v_cndmask_b32_e64 v89, v89, 0, s[20:21]
	v_cndmask_b32_e64 v86, v86, 0, s[14:15]
	v_cndmask_b32_e64 v87, v87, 0, s[16:17]
	v_cndmask_b32_e64 v84, v84, 0, s[10:11]
	v_cndmask_b32_e64 v85, v85, 0, s[12:13]
	v_cndmask_b32_e64 v82, v82, 0, s[94:95]
	v_mfma_f32_32x32x16_bf16 v[90:105], v[176:179], v[184:187], v[90:105]
	v_cndmask_b32_e64 v83, v83, 0, s[8:9]
	v_mfma_f32_32x32x16_bf16 v[90:105], v[122:125], v[192:195], v[90:105]
	v_mfma_f32_32x32x16_bf16 v[90:105], v[180:183], v[200:203], v[90:105]
	v_mfma_f32_32x32x16_bf16 v[90:105], v[188:191], v[208:211], v[90:105]
	v_mfma_f32_32x32x16_bf16 v[90:105], v[196:199], v[216:219], v[90:105]
	v_mfma_f32_32x32x16_bf16 v[90:105], v[204:207], v[224:227], v[90:105]
	v_mfma_f32_32x32x16_bf16 v[90:105], v[212:215], v[232:235], v[90:105]
	v_cndmask_b32_e64 v66, v66, 0, s[94:95]
	v_cndmask_b32_e64 v67, v67, 0, s[8:9]
	v_cndmask_b32_e64 v190, v74, 0, s[22:23]
	v_cndmask_b32_e64 v191, v75, 0, s[24:25]
	v_and_b32_sdwa v74, v67, v169 dst_sel:DWORD dst_unused:UNUSED_PAD src0_sel:WORD_1 src1_sel:DWORD
	v_and_b32_sdwa v75, v66, v169 dst_sel:DWORD dst_unused:UNUSED_PAD src0_sel:WORD_1 src1_sel:DWORD
	v_add3_u32 v66, v66, v75, s33
	v_add3_u32 v74, v67, v74, s33
	s_nop 3
	v_and_b32_sdwa v67, v91, v169 dst_sel:DWORD dst_unused:UNUSED_PAD src0_sel:WORD_1 src1_sel:DWORD
	v_and_b32_sdwa v75, v90, v169 dst_sel:DWORD dst_unused:UNUSED_PAD src0_sel:WORD_1 src1_sel:DWORD
	v_cndmask_b32_e64 v68, v68, 0, s[10:11]
	v_cndmask_b32_e64 v69, v69, 0, s[12:13]
	v_add3_u32 v90, v90, v75, s33
	v_add3_u32 v91, v91, v67, s33
	v_and_b32_sdwa v67, v83, v169 dst_sel:DWORD dst_unused:UNUSED_PAD src0_sel:WORD_1 src1_sel:DWORD
	v_and_b32_sdwa v75, v82, v169 dst_sel:DWORD dst_unused:UNUSED_PAD src0_sel:WORD_1 src1_sel:DWORD
	v_add3_u32 v180, v82, v75, s33
	v_add3_u32 v192, v83, v67, s33
	v_and_b32_sdwa v67, v69, v169 dst_sel:DWORD dst_unused:UNUSED_PAD src0_sel:WORD_1 src1_sel:DWORD
	v_and_b32_sdwa v75, v68, v169 dst_sel:DWORD dst_unused:UNUSED_PAD src0_sel:WORD_1 src1_sel:DWORD
	v_add3_u32 v75, v68, v75, s33
	v_add3_u32 v67, v69, v67, s33
	v_and_b32_sdwa v68, v93, v169 dst_sel:DWORD dst_unused:UNUSED_PAD src0_sel:WORD_1 src1_sel:DWORD
	v_and_b32_sdwa v69, v92, v169 dst_sel:DWORD dst_unused:UNUSED_PAD src0_sel:WORD_1 src1_sel:DWORD
	v_cndmask_b32_e64 v70, v70, 0, s[14:15]
	v_cndmask_b32_e64 v71, v71, 0, s[16:17]
	v_add3_u32 v92, v92, v69, s33
	v_add3_u32 v93, v93, v68, s33
	v_and_b32_sdwa v68, v85, v169 dst_sel:DWORD dst_unused:UNUSED_PAD src0_sel:WORD_1 src1_sel:DWORD
	v_and_b32_sdwa v69, v84, v169 dst_sel:DWORD dst_unused:UNUSED_PAD src0_sel:WORD_1 src1_sel:DWORD
	v_add3_u32 v181, v84, v69, s33
	v_add3_u32 v193, v85, v68, s33
	v_and_b32_sdwa v68, v71, v169 dst_sel:DWORD dst_unused:UNUSED_PAD src0_sel:WORD_1 src1_sel:DWORD
	v_and_b32_sdwa v69, v70, v169 dst_sel:DWORD dst_unused:UNUSED_PAD src0_sel:WORD_1 src1_sel:DWORD
	v_add3_u32 v70, v70, v69, s33
	v_add3_u32 v68, v71, v68, s33
	v_and_b32_sdwa v69, v95, v169 dst_sel:DWORD dst_unused:UNUSED_PAD src0_sel:WORD_1 src1_sel:DWORD
	v_and_b32_sdwa v71, v94, v169 dst_sel:DWORD dst_unused:UNUSED_PAD src0_sel:WORD_1 src1_sel:DWORD
	v_cndmask_b32_e64 v72, v72, 0, s[18:19]
	v_cndmask_b32_e64 v73, v73, 0, s[20:21]
	v_add3_u32 v94, v94, v71, s33
	v_add3_u32 v95, v95, v69, s33
	v_and_b32_sdwa v69, v87, v169 dst_sel:DWORD dst_unused:UNUSED_PAD src0_sel:WORD_1 src1_sel:DWORD
	v_and_b32_sdwa v71, v86, v169 dst_sel:DWORD dst_unused:UNUSED_PAD src0_sel:WORD_1 src1_sel:DWORD
	v_add3_u32 v182, v86, v71, s33
	v_add3_u32 v194, v87, v69, s33
	v_and_b32_sdwa v69, v73, v169 dst_sel:DWORD dst_unused:UNUSED_PAD src0_sel:WORD_1 src1_sel:DWORD
	v_and_b32_sdwa v71, v72, v169 dst_sel:DWORD dst_unused:UNUSED_PAD src0_sel:WORD_1 src1_sel:DWORD
	v_add3_u32 v71, v72, v71, s33
	v_add3_u32 v69, v73, v69, s33
	v_and_b32_sdwa v72, v97, v169 dst_sel:DWORD dst_unused:UNUSED_PAD src0_sel:WORD_1 src1_sel:DWORD
	v_and_b32_sdwa v73, v96, v169 dst_sel:DWORD dst_unused:UNUSED_PAD src0_sel:WORD_1 src1_sel:DWORD
	v_add3_u32 v86, v96, v73, s33
	v_add3_u32 v87, v97, v72, s33
	v_and_b32_sdwa v72, v89, v169 dst_sel:DWORD dst_unused:UNUSED_PAD src0_sel:WORD_1 src1_sel:DWORD
	v_and_b32_sdwa v73, v88, v169 dst_sel:DWORD dst_unused:UNUSED_PAD src0_sel:WORD_1 src1_sel:DWORD
	v_add3_u32 v183, v88, v73, s33
	v_add3_u32 v195, v89, v72, s33
	v_add_u32_e32 v196, 0xd000, v170
	v_perm_b32 v69, v69, v71, s50
	v_perm_b32 v68, v68, v70, s50
	v_perm_b32 v67, v67, v75, s50
	v_perm_b32 v66, v74, v66, s50
	v_perm_b32 v89, v87, v86, s50
	v_perm_b32 v88, v95, v94, s50
	v_perm_b32 v87, v93, v92, s50
	v_perm_b32 v86, v91, v90, s50
	ds_read2_b64 v[122:125], v196 offset0:8 offset1:10
	ds_read2_b64 v[82:85], v196 offset1:2
	ds_read2_b64 v[176:179], v196 offset0:4 offset1:6
	v_cndmask_b32_e64 v184, v80, 0, s[38:39]
	v_cndmask_b32_e64 v185, v81, 0, s[6:7]
	v_cndmask_b32_e64 v186, v78, 0, s[34:35]
	v_cndmask_b32_e64 v187, v79, 0, s[36:37]
	v_cndmask_b32_e64 v188, v76, 0, s[26:27]
	v_cndmask_b32_e64 v189, v77, 0, s[28:29]
	s_waitcnt lgkmcnt(1)
	v_mfma_f32_32x32x16_bf16 v[66:81], v[66:69], v[82:85], 0
	v_perm_b32 v183, v195, v183, s50
	v_perm_b32 v182, v194, v182, s50
	v_perm_b32 v181, v193, v181, s50
	v_perm_b32 v180, v192, v180, s50
	v_mfma_f32_32x32x16_bf16 v[82:97], v[86:89], v[82:85], 0
	s_nop 0
	v_mfma_f32_32x32x16_bf16 v[82:97], v[180:183], v[122:125], v[82:97]
	v_and_b32_sdwa v124, v99, v169 dst_sel:DWORD dst_unused:UNUSED_PAD src0_sel:WORD_1 src1_sel:DWORD
	v_and_b32_sdwa v125, v98, v169 dst_sel:DWORD dst_unused:UNUSED_PAD src0_sel:WORD_1 src1_sel:DWORD
	v_add3_u32 v125, v98, v125, s33
	v_add3_u32 v124, v99, v124, s33
	v_and_b32_sdwa v98, v230, v169 dst_sel:DWORD dst_unused:UNUSED_PAD src0_sel:WORD_1 src1_sel:DWORD
	v_and_b32_sdwa v99, v229, v169 dst_sel:DWORD dst_unused:UNUSED_PAD src0_sel:WORD_1 src1_sel:DWORD
	v_add3_u32 v180, v229, v99, s33
	v_add3_u32 v181, v230, v98, s33
	v_and_b32_sdwa v98, v189, v169 dst_sel:DWORD dst_unused:UNUSED_PAD src0_sel:WORD_1 src1_sel:DWORD
	v_and_b32_sdwa v99, v188, v169 dst_sel:DWORD dst_unused:UNUSED_PAD src0_sel:WORD_1 src1_sel:DWORD
	v_add3_u32 v182, v188, v99, s33
	v_add3_u32 v183, v189, v98, s33
	v_and_b32_sdwa v98, v101, v169 dst_sel:DWORD dst_unused:UNUSED_PAD src0_sel:WORD_1 src1_sel:DWORD
	v_and_b32_sdwa v99, v100, v169 dst_sel:DWORD dst_unused:UNUSED_PAD src0_sel:WORD_1 src1_sel:DWORD
	v_and_b32_sdwa v122, v191, v169 dst_sel:DWORD dst_unused:UNUSED_PAD src0_sel:WORD_1 src1_sel:DWORD
	v_and_b32_sdwa v123, v190, v169 dst_sel:DWORD dst_unused:UNUSED_PAD src0_sel:WORD_1 src1_sel:DWORD
	v_add3_u32 v188, v100, v99, s33
	v_add3_u32 v189, v101, v98, s33
	v_and_b32_sdwa v98, v228, v169 dst_sel:DWORD dst_unused:UNUSED_PAD src0_sel:WORD_1 src1_sel:DWORD
	v_and_b32_sdwa v99, v223, v169 dst_sel:DWORD dst_unused:UNUSED_PAD src0_sel:WORD_1 src1_sel:DWORD
	v_add3_u32 v123, v190, v123, s33
	v_add3_u32 v122, v191, v122, s33
	v_add3_u32 v190, v223, v99, s33
	v_add3_u32 v191, v228, v98, s33
	v_and_b32_sdwa v98, v187, v169 dst_sel:DWORD dst_unused:UNUSED_PAD src0_sel:WORD_1 src1_sel:DWORD
	v_and_b32_sdwa v99, v186, v169 dst_sel:DWORD dst_unused:UNUSED_PAD src0_sel:WORD_1 src1_sel:DWORD
	v_add3_u32 v186, v186, v99, s33
	v_add3_u32 v187, v187, v98, s33
	v_and_b32_sdwa v98, v103, v169 dst_sel:DWORD dst_unused:UNUSED_PAD src0_sel:WORD_1 src1_sel:DWORD
	v_and_b32_sdwa v99, v102, v169 dst_sel:DWORD dst_unused:UNUSED_PAD src0_sel:WORD_1 src1_sel:DWORD
	v_add3_u32 v192, v102, v99, s33
	v_add3_u32 v193, v103, v98, s33
	v_and_b32_sdwa v98, v222, v169 dst_sel:DWORD dst_unused:UNUSED_PAD src0_sel:WORD_1 src1_sel:DWORD
	v_and_b32_sdwa v99, v221, v169 dst_sel:DWORD dst_unused:UNUSED_PAD src0_sel:WORD_1 src1_sel:DWORD
	v_add3_u32 v194, v221, v99, s33
	v_add3_u32 v195, v222, v98, s33
	v_and_b32_sdwa v98, v185, v169 dst_sel:DWORD dst_unused:UNUSED_PAD src0_sel:WORD_1 src1_sel:DWORD
	v_and_b32_sdwa v99, v184, v169 dst_sel:DWORD dst_unused:UNUSED_PAD src0_sel:WORD_1 src1_sel:DWORD
	v_add3_u32 v102, v184, v99, s33
	v_add3_u32 v103, v185, v98, s33
	v_and_b32_sdwa v98, v105, v169 dst_sel:DWORD dst_unused:UNUSED_PAD src0_sel:WORD_1 src1_sel:DWORD
	v_and_b32_sdwa v99, v104, v169 dst_sel:DWORD dst_unused:UNUSED_PAD src0_sel:WORD_1 src1_sel:DWORD
	v_add3_u32 v184, v104, v99, s33
	v_add3_u32 v185, v105, v98, s33
	v_perm_b32 v105, v103, v102, s50
	v_perm_b32 v104, v187, v186, s50
	v_perm_b32 v103, v183, v182, s50
	v_perm_b32 v102, v122, v123, s50
	v_and_b32_sdwa v98, v220, v169 dst_sel:DWORD dst_unused:UNUSED_PAD src0_sel:WORD_1 src1_sel:DWORD
	v_and_b32_sdwa v99, v175, v169 dst_sel:DWORD dst_unused:UNUSED_PAD src0_sel:WORD_1 src1_sel:DWORD
	s_waitcnt lgkmcnt(0)
	v_mfma_f32_32x32x16_bf16 v[66:81], v[102:105], v[176:179], v[66:81]
	v_perm_b32 v105, v185, v184, s50
	v_perm_b32 v104, v193, v192, s50
	v_perm_b32 v103, v189, v188, s50
	v_perm_b32 v102, v124, v125, s50
	v_add3_u32 v175, v175, v99, s33
	v_add3_u32 v197, v220, v98, s33
	ds_read2_b64 v[98:101], v196 offset0:12 offset1:14
	v_mfma_f32_32x32x16_bf16 v[82:97], v[102:105], v[176:179], v[82:97]
	v_perm_b32 v105, v197, v175, s50
	v_perm_b32 v104, v195, v194, s50
	v_perm_b32 v103, v191, v190, s50
	v_perm_b32 v102, v181, v180, s50
	s_waitcnt lgkmcnt(0)
	s_nop 0
	v_mfma_f32_32x32x16_bf16 v[82:97], v[102:105], v[98:101], v[82:97]
	v_and_b32_sdwa v98, v3, v169 dst_sel:DWORD dst_unused:UNUSED_PAD src0_sel:WORD_1 src1_sel:DWORD
	v_and_b32_sdwa v99, v2, v169 dst_sel:DWORD dst_unused:UNUSED_PAD src0_sel:WORD_1 src1_sel:DWORD
	v_add3_u32 v102, v2, v99, s33
	v_add3_u32 v122, v3, v98, s33
	v_and_b32_sdwa v98, v5, v169 dst_sel:DWORD dst_unused:UNUSED_PAD src0_sel:WORD_1 src1_sel:DWORD
	v_and_b32_sdwa v99, v4, v169 dst_sel:DWORD dst_unused:UNUSED_PAD src0_sel:WORD_1 src1_sel:DWORD
	v_add3_u32 v103, v4, v99, s33
	v_add3_u32 v123, v5, v98, s33
	v_and_b32_sdwa v98, v7, v169 dst_sel:DWORD dst_unused:UNUSED_PAD src0_sel:WORD_1 src1_sel:DWORD
	v_and_b32_sdwa v99, v6, v169 dst_sel:DWORD dst_unused:UNUSED_PAD src0_sel:WORD_1 src1_sel:DWORD
	v_add3_u32 v104, v6, v99, s33
	v_add3_u32 v124, v7, v98, s33
	ds_read2_b64 v[98:101], v162 offset1:2
	v_and_b32_sdwa v105, v9, v169 dst_sel:DWORD dst_unused:UNUSED_PAD src0_sel:WORD_1 src1_sel:DWORD
	v_and_b32_sdwa v125, v8, v169 dst_sel:DWORD dst_unused:UNUSED_PAD src0_sel:WORD_1 src1_sel:DWORD
	v_add3_u32 v125, v8, v125, s33
	v_add3_u32 v105, v9, v105, s33
	v_add_u32_e32 v175, 0x2000, v162
	v_perm_b32 v105, v105, v125, s50
	v_perm_b32 v104, v124, v104, s50
	v_perm_b32 v103, v123, v103, s50
	v_perm_b32 v102, v122, v102, s50
	s_waitcnt lgkmcnt(0)
	s_nop 0
	v_mfma_f32_32x32x16_bf16 v[66:81], v[98:101], v[102:105], v[66:81]
	ds_read2_b64 v[98:101], v175 offset0:64 offset1:66
	ds_read2_b64 v[122:125], v162 offset0:4 offset1:6
	s_waitcnt lgkmcnt(1)
	v_mfma_f32_32x32x16_bf16 v[82:97], v[98:101], v[102:105], v[82:97]
	v_and_b32_sdwa v99, v10, v169 dst_sel:DWORD dst_unused:UNUSED_PAD src0_sel:WORD_1 src1_sel:DWORD
	v_and_b32_sdwa v100, v12, v169 dst_sel:DWORD dst_unused:UNUSED_PAD src0_sel:WORD_1 src1_sel:DWORD
	v_and_b32_sdwa v101, v14, v169 dst_sel:DWORD dst_unused:UNUSED_PAD src0_sel:WORD_1 src1_sel:DWORD
	v_and_b32_sdwa v98, v11, v169 dst_sel:DWORD dst_unused:UNUSED_PAD src0_sel:WORD_1 src1_sel:DWORD
	v_add3_u32 v102, v10, v99, s33
	v_and_b32_sdwa v99, v13, v169 dst_sel:DWORD dst_unused:UNUSED_PAD src0_sel:WORD_1 src1_sel:DWORD
	v_add3_u32 v103, v12, v100, s33
	v_and_b32_sdwa v100, v15, v169 dst_sel:DWORD dst_unused:UNUSED_PAD src0_sel:WORD_1 src1_sel:DWORD
	v_add3_u32 v104, v14, v101, s33
	v_and_b32_sdwa v101, v17, v169 dst_sel:DWORD dst_unused:UNUSED_PAD src0_sel:WORD_1 src1_sel:DWORD
	v_and_b32_sdwa v105, v16, v169 dst_sel:DWORD dst_unused:UNUSED_PAD src0_sel:WORD_1 src1_sel:DWORD
	v_add3_u32 v98, v11, v98, s33
	v_add3_u32 v99, v13, v99, s33
	v_add3_u32 v100, v15, v100, s33
	v_add3_u32 v105, v16, v105, s33
	v_add3_u32 v101, v17, v101, s33
	v_perm_b32 v101, v101, v105, s50
	v_perm_b32 v100, v100, v104, s50
	v_perm_b32 v99, v99, v103, s50
	v_perm_b32 v98, v98, v102, s50
	ds_read2_b64 v[102:105], v175 offset0:68 offset1:70
	s_waitcnt lgkmcnt(1)
	v_mfma_f32_32x32x16_bf16 v[66:81], v[122:125], v[98:101], v[66:81]
	s_waitcnt lgkmcnt(0)
	v_mfma_f32_32x32x16_bf16 v[82:97], v[102:105], v[98:101], v[82:97]
	v_and_b32_sdwa v98, v19, v169 dst_sel:DWORD dst_unused:UNUSED_PAD src0_sel:WORD_1 src1_sel:DWORD
	v_and_b32_sdwa v99, v18, v169 dst_sel:DWORD dst_unused:UNUSED_PAD src0_sel:WORD_1 src1_sel:DWORD
	v_add3_u32 v102, v18, v99, s33
	v_add3_u32 v122, v19, v98, s33
	v_and_b32_sdwa v98, v21, v169 dst_sel:DWORD dst_unused:UNUSED_PAD src0_sel:WORD_1 src1_sel:DWORD
	v_and_b32_sdwa v99, v20, v169 dst_sel:DWORD dst_unused:UNUSED_PAD src0_sel:WORD_1 src1_sel:DWORD
	v_add3_u32 v103, v20, v99, s33
	v_add3_u32 v123, v21, v98, s33
	v_and_b32_sdwa v98, v23, v169 dst_sel:DWORD dst_unused:UNUSED_PAD src0_sel:WORD_1 src1_sel:DWORD
	v_and_b32_sdwa v99, v22, v169 dst_sel:DWORD dst_unused:UNUSED_PAD src0_sel:WORD_1 src1_sel:DWORD
	v_add3_u32 v104, v22, v99, s33
	v_add3_u32 v124, v23, v98, s33
	ds_read2_b64 v[98:101], v162 offset0:8 offset1:10
	v_and_b32_sdwa v105, v25, v169 dst_sel:DWORD dst_unused:UNUSED_PAD src0_sel:WORD_1 src1_sel:DWORD
	v_and_b32_sdwa v125, v24, v169 dst_sel:DWORD dst_unused:UNUSED_PAD src0_sel:WORD_1 src1_sel:DWORD
	v_add3_u32 v125, v24, v125, s33
	v_add3_u32 v105, v25, v105, s33
	v_perm_b32 v105, v105, v125, s50
	v_perm_b32 v104, v124, v104, s50
	v_perm_b32 v103, v123, v103, s50
	v_perm_b32 v102, v122, v102, s50
	s_waitcnt lgkmcnt(0)
	s_nop 0
	v_mfma_f32_32x32x16_bf16 v[66:81], v[98:101], v[102:105], v[66:81]
	ds_read2_b64 v[98:101], v175 offset0:72 offset1:74
	ds_read2_b64 v[122:125], v162 offset0:12 offset1:14
	s_waitcnt lgkmcnt(1)
	v_mfma_f32_32x32x16_bf16 v[82:97], v[98:101], v[102:105], v[82:97]
	v_and_b32_sdwa v99, v26, v169 dst_sel:DWORD dst_unused:UNUSED_PAD src0_sel:WORD_1 src1_sel:DWORD
	v_and_b32_sdwa v100, v28, v169 dst_sel:DWORD dst_unused:UNUSED_PAD src0_sel:WORD_1 src1_sel:DWORD
	v_and_b32_sdwa v101, v30, v169 dst_sel:DWORD dst_unused:UNUSED_PAD src0_sel:WORD_1 src1_sel:DWORD
	v_and_b32_sdwa v98, v27, v169 dst_sel:DWORD dst_unused:UNUSED_PAD src0_sel:WORD_1 src1_sel:DWORD
	v_add3_u32 v102, v26, v99, s33
	v_and_b32_sdwa v99, v29, v169 dst_sel:DWORD dst_unused:UNUSED_PAD src0_sel:WORD_1 src1_sel:DWORD
	v_add3_u32 v103, v28, v100, s33
	v_and_b32_sdwa v100, v31, v169 dst_sel:DWORD dst_unused:UNUSED_PAD src0_sel:WORD_1 src1_sel:DWORD
	v_add3_u32 v104, v30, v101, s33
	v_and_b32_sdwa v101, v33, v169 dst_sel:DWORD dst_unused:UNUSED_PAD src0_sel:WORD_1 src1_sel:DWORD
	v_and_b32_sdwa v105, v32, v169 dst_sel:DWORD dst_unused:UNUSED_PAD src0_sel:WORD_1 src1_sel:DWORD
	v_add3_u32 v98, v27, v98, s33
	v_add3_u32 v99, v29, v99, s33
	v_add3_u32 v100, v31, v100, s33
	v_add3_u32 v105, v32, v105, s33
	v_add3_u32 v101, v33, v101, s33
	v_perm_b32 v101, v101, v105, s50
	v_perm_b32 v100, v100, v104, s50
	v_perm_b32 v99, v99, v103, s50
	v_perm_b32 v98, v98, v102, s50
	ds_read2_b64 v[102:105], v175 offset0:76 offset1:78
	s_waitcnt lgkmcnt(1)
	v_mfma_f32_32x32x16_bf16 v[66:81], v[122:125], v[98:101], v[66:81]
	s_waitcnt lgkmcnt(0)
	v_mfma_f32_32x32x16_bf16 v[82:97], v[102:105], v[98:101], v[82:97]
	v_and_b32_sdwa v98, v35, v169 dst_sel:DWORD dst_unused:UNUSED_PAD src0_sel:WORD_1 src1_sel:DWORD
	v_and_b32_sdwa v99, v34, v169 dst_sel:DWORD dst_unused:UNUSED_PAD src0_sel:WORD_1 src1_sel:DWORD
	v_add3_u32 v102, v34, v99, s33
	v_add3_u32 v122, v35, v98, s33
	v_and_b32_sdwa v98, v37, v169 dst_sel:DWORD dst_unused:UNUSED_PAD src0_sel:WORD_1 src1_sel:DWORD
	v_and_b32_sdwa v99, v36, v169 dst_sel:DWORD dst_unused:UNUSED_PAD src0_sel:WORD_1 src1_sel:DWORD
	v_add3_u32 v103, v36, v99, s33
	v_add3_u32 v123, v37, v98, s33
	v_and_b32_sdwa v98, v39, v169 dst_sel:DWORD dst_unused:UNUSED_PAD src0_sel:WORD_1 src1_sel:DWORD
	v_and_b32_sdwa v99, v38, v169 dst_sel:DWORD dst_unused:UNUSED_PAD src0_sel:WORD_1 src1_sel:DWORD
	v_add3_u32 v104, v38, v99, s33
	v_add3_u32 v124, v39, v98, s33
	ds_read2_b64 v[98:101], v162 offset0:16 offset1:18
	v_and_b32_sdwa v105, v41, v169 dst_sel:DWORD dst_unused:UNUSED_PAD src0_sel:WORD_1 src1_sel:DWORD
	v_and_b32_sdwa v125, v40, v169 dst_sel:DWORD dst_unused:UNUSED_PAD src0_sel:WORD_1 src1_sel:DWORD
	v_add3_u32 v125, v40, v125, s33
	v_add3_u32 v105, v41, v105, s33
	v_perm_b32 v105, v105, v125, s50
	v_perm_b32 v104, v124, v104, s50
	v_perm_b32 v103, v123, v103, s50
	v_perm_b32 v102, v122, v102, s50
	s_waitcnt lgkmcnt(0)
	s_nop 0
	v_mfma_f32_32x32x16_bf16 v[66:81], v[98:101], v[102:105], v[66:81]
	ds_read2_b64 v[98:101], v175 offset0:80 offset1:82
	ds_read2_b64 v[122:125], v162 offset0:20 offset1:22
	s_waitcnt lgkmcnt(1)
	v_mfma_f32_32x32x16_bf16 v[82:97], v[98:101], v[102:105], v[82:97]
	v_and_b32_sdwa v99, v42, v169 dst_sel:DWORD dst_unused:UNUSED_PAD src0_sel:WORD_1 src1_sel:DWORD
	v_and_b32_sdwa v100, v44, v169 dst_sel:DWORD dst_unused:UNUSED_PAD src0_sel:WORD_1 src1_sel:DWORD
	v_and_b32_sdwa v101, v46, v169 dst_sel:DWORD dst_unused:UNUSED_PAD src0_sel:WORD_1 src1_sel:DWORD
	v_and_b32_sdwa v98, v43, v169 dst_sel:DWORD dst_unused:UNUSED_PAD src0_sel:WORD_1 src1_sel:DWORD
	v_add3_u32 v102, v42, v99, s33
	v_and_b32_sdwa v99, v45, v169 dst_sel:DWORD dst_unused:UNUSED_PAD src0_sel:WORD_1 src1_sel:DWORD
	v_add3_u32 v103, v44, v100, s33
	v_and_b32_sdwa v100, v47, v169 dst_sel:DWORD dst_unused:UNUSED_PAD src0_sel:WORD_1 src1_sel:DWORD
	v_add3_u32 v104, v46, v101, s33
	v_and_b32_sdwa v101, v49, v169 dst_sel:DWORD dst_unused:UNUSED_PAD src0_sel:WORD_1 src1_sel:DWORD
	v_and_b32_sdwa v105, v48, v169 dst_sel:DWORD dst_unused:UNUSED_PAD src0_sel:WORD_1 src1_sel:DWORD
	v_add3_u32 v98, v43, v98, s33
	v_add3_u32 v99, v45, v99, s33
	v_add3_u32 v100, v47, v100, s33
	v_add3_u32 v105, v48, v105, s33
	v_add3_u32 v101, v49, v101, s33
	v_perm_b32 v101, v101, v105, s50
	v_perm_b32 v100, v100, v104, s50
	v_perm_b32 v99, v99, v103, s50
	v_perm_b32 v98, v98, v102, s50
	ds_read2_b64 v[102:105], v175 offset0:84 offset1:86
	s_waitcnt lgkmcnt(1)
	v_mfma_f32_32x32x16_bf16 v[66:81], v[122:125], v[98:101], v[66:81]
	s_waitcnt lgkmcnt(0)
	v_mfma_f32_32x32x16_bf16 v[82:97], v[102:105], v[98:101], v[82:97]
	v_and_b32_sdwa v98, v51, v169 dst_sel:DWORD dst_unused:UNUSED_PAD src0_sel:WORD_1 src1_sel:DWORD
	v_and_b32_sdwa v99, v50, v169 dst_sel:DWORD dst_unused:UNUSED_PAD src0_sel:WORD_1 src1_sel:DWORD
	v_add3_u32 v102, v50, v99, s33
	v_add3_u32 v122, v51, v98, s33
	v_and_b32_sdwa v98, v53, v169 dst_sel:DWORD dst_unused:UNUSED_PAD src0_sel:WORD_1 src1_sel:DWORD
	v_and_b32_sdwa v99, v52, v169 dst_sel:DWORD dst_unused:UNUSED_PAD src0_sel:WORD_1 src1_sel:DWORD
	v_add3_u32 v103, v52, v99, s33
	v_add3_u32 v123, v53, v98, s33
	v_and_b32_sdwa v98, v55, v169 dst_sel:DWORD dst_unused:UNUSED_PAD src0_sel:WORD_1 src1_sel:DWORD
	v_and_b32_sdwa v99, v54, v169 dst_sel:DWORD dst_unused:UNUSED_PAD src0_sel:WORD_1 src1_sel:DWORD
	v_add3_u32 v104, v54, v99, s33
	v_add3_u32 v124, v55, v98, s33
	ds_read2_b64 v[98:101], v162 offset0:24 offset1:26
	v_and_b32_sdwa v105, v57, v169 dst_sel:DWORD dst_unused:UNUSED_PAD src0_sel:WORD_1 src1_sel:DWORD
	v_and_b32_sdwa v125, v56, v169 dst_sel:DWORD dst_unused:UNUSED_PAD src0_sel:WORD_1 src1_sel:DWORD
	v_add3_u32 v125, v56, v125, s33
	v_add3_u32 v105, v57, v105, s33
	v_perm_b32 v105, v105, v125, s50
	v_perm_b32 v104, v124, v104, s50
	v_perm_b32 v103, v123, v103, s50
	v_perm_b32 v102, v122, v102, s50
	s_waitcnt lgkmcnt(0)
	s_nop 0
	v_mfma_f32_32x32x16_bf16 v[66:81], v[98:101], v[102:105], v[66:81]
	ds_read2_b64 v[122:125], v175 offset0:88 offset1:90
	ds_read2_b64 v[98:101], v162 offset0:28 offset1:30
	s_waitcnt lgkmcnt(1)
	v_mfma_f32_32x32x16_bf16 v[82:97], v[122:125], v[102:105], v[82:97]
	v_and_b32_sdwa v102, v59, v169 dst_sel:DWORD dst_unused:UNUSED_PAD src0_sel:WORD_1 src1_sel:DWORD
	v_and_b32_sdwa v103, v58, v169 dst_sel:DWORD dst_unused:UNUSED_PAD src0_sel:WORD_1 src1_sel:DWORD
	v_add3_u32 v122, v58, v103, s33
	v_add3_u32 v176, v59, v102, s33
	v_and_b32_sdwa v102, v61, v169 dst_sel:DWORD dst_unused:UNUSED_PAD src0_sel:WORD_1 src1_sel:DWORD
	v_and_b32_sdwa v103, v60, v169 dst_sel:DWORD dst_unused:UNUSED_PAD src0_sel:WORD_1 src1_sel:DWORD
	v_add3_u32 v123, v60, v103, s33
	v_add3_u32 v177, v61, v102, s33
	v_and_b32_sdwa v102, v63, v169 dst_sel:DWORD dst_unused:UNUSED_PAD src0_sel:WORD_1 src1_sel:DWORD
	v_and_b32_sdwa v103, v62, v169 dst_sel:DWORD dst_unused:UNUSED_PAD src0_sel:WORD_1 src1_sel:DWORD
	v_add3_u32 v124, v62, v103, s33
	v_add3_u32 v178, v63, v102, s33
	v_and_b32_sdwa v102, v65, v169 dst_sel:DWORD dst_unused:UNUSED_PAD src0_sel:WORD_1 src1_sel:DWORD
	v_and_b32_sdwa v103, v64, v169 dst_sel:DWORD dst_unused:UNUSED_PAD src0_sel:WORD_1 src1_sel:DWORD
	v_add3_u32 v125, v64, v103, s33
	v_add3_u32 v179, v65, v102, s33
	ds_read2_b64 v[102:105], v175 offset0:92 offset1:94
	v_perm_b32 v125, v179, v125, s50
	v_perm_b32 v124, v178, v124, s50
	v_perm_b32 v123, v177, v123, s50
	v_perm_b32 v122, v176, v122, s50
	ds_read_b128 v[176:179], v163 offset:34816
	ds_read_b128 v[180:183], v163 offset:34848
	ds_read_b128 v[184:187], v174 offset:53248
	ds_read_b128 v[188:191], v174 offset:53280
	s_waitcnt lgkmcnt(1)
	v_mfma_f32_32x32x16_bf16 v[2:17], v[176:179], v[184:187], v[2:17]
	s_waitcnt lgkmcnt(0)
	v_mfma_f32_32x32x16_bf16 v[2:17], v[180:183], v[188:191], v[2:17]
	ds_read_b128 v[176:179], v163 offset:34880
	ds_read_b128 v[180:183], v174 offset:53312
	s_waitcnt lgkmcnt(0)
	v_mfma_f32_32x32x16_bf16 v[2:17], v[176:179], v[180:183], v[2:17]
	ds_read_b128 v[176:179], v163 offset:34912
	ds_read_b128 v[180:183], v174 offset:53344
	s_waitcnt lgkmcnt(0)
	v_mfma_f32_32x32x16_bf16 v[2:17], v[176:179], v[180:183], v[2:17]
	ds_read_b128 v[176:179], v155
	ds_read_b128 v[180:183], v155 offset:32
	s_waitcnt lgkmcnt(1)
	s_nop 8
	v_pk_mul_f32 v[2:3], v[176:177], v[2:3]
	v_pk_mul_f32 v[4:5], v[4:5], v[178:179]
	ds_read_b128 v[176:179], v155 offset:64
	s_waitcnt lgkmcnt(1)
	v_pk_mul_f32 v[6:7], v[6:7], v[180:181]
	v_pk_mul_f32 v[8:9], v[8:9], v[182:183]
	s_waitcnt lgkmcnt(0)
	v_pk_mul_f32 v[10:11], v[10:11], v[176:177]
	v_pk_mul_f32 v[12:13], v[12:13], v[178:179]
	ds_read_b128 v[176:179], v155 offset:96
	s_waitcnt lgkmcnt(0)
	v_pk_mul_f32 v[14:15], v[14:15], v[176:177]
	v_pk_mul_f32 v[16:17], v[16:17], v[178:179]
	ds_read_b128 v[176:179], v163 offset:39424
	ds_read_b128 v[180:183], v163 offset:39456
	ds_read_b128 v[184:187], v174 offset:53248
	ds_read_b128 v[188:191], v174 offset:53280
	s_waitcnt lgkmcnt(1)
	v_mfma_f32_32x32x16_bf16 v[18:33], v[176:179], v[184:187], v[18:33]
	s_waitcnt lgkmcnt(0)
	v_mfma_f32_32x32x16_bf16 v[18:33], v[180:183], v[188:191], v[18:33]
	ds_read_b128 v[176:179], v163 offset:39488
	ds_read_b128 v[180:183], v174 offset:53312
	s_waitcnt lgkmcnt(0)
	v_mfma_f32_32x32x16_bf16 v[18:33], v[176:179], v[180:183], v[18:33]
	ds_read_b128 v[176:179], v163 offset:39520
	ds_read_b128 v[180:183], v174 offset:53344
	s_waitcnt lgkmcnt(0)
	v_mfma_f32_32x32x16_bf16 v[18:33], v[176:179], v[180:183], v[18:33]
	ds_read_b128 v[176:179], v155 offset:128
	ds_read_b128 v[180:183], v155 offset:160
	s_waitcnt lgkmcnt(1)
	s_nop 8
	v_pk_mul_f32 v[18:19], v[176:177], v[18:19]
	v_pk_mul_f32 v[20:21], v[20:21], v[178:179]
	ds_read_b128 v[176:179], v155 offset:192
	s_waitcnt lgkmcnt(1)
	v_pk_mul_f32 v[22:23], v[22:23], v[180:181]
	v_pk_mul_f32 v[24:25], v[24:25], v[182:183]
	s_waitcnt lgkmcnt(0)
	v_pk_mul_f32 v[26:27], v[26:27], v[176:177]
	v_pk_mul_f32 v[28:29], v[28:29], v[178:179]
	ds_read_b128 v[176:179], v155 offset:224
	s_waitcnt lgkmcnt(0)
	v_pk_mul_f32 v[30:31], v[30:31], v[176:177]
	v_pk_mul_f32 v[32:33], v[32:33], v[178:179]
	ds_read_b128 v[176:179], v163 offset:44032
	ds_read_b128 v[180:183], v163 offset:44064
	ds_read_b128 v[184:187], v174 offset:53248
	ds_read_b128 v[188:191], v174 offset:53280
	s_waitcnt lgkmcnt(1)
	v_mfma_f32_32x32x16_bf16 v[34:49], v[176:179], v[184:187], v[34:49]
	s_waitcnt lgkmcnt(0)
	v_mfma_f32_32x32x16_bf16 v[34:49], v[180:183], v[188:191], v[34:49]
	ds_read_b128 v[176:179], v163 offset:44096
	ds_read_b128 v[180:183], v174 offset:53312
	s_waitcnt lgkmcnt(0)
	v_mfma_f32_32x32x16_bf16 v[34:49], v[176:179], v[180:183], v[34:49]
	ds_read_b128 v[176:179], v163 offset:44128
	ds_read_b128 v[180:183], v174 offset:53344
	s_waitcnt lgkmcnt(0)
	v_mfma_f32_32x32x16_bf16 v[34:49], v[176:179], v[180:183], v[34:49]
	ds_read_b128 v[176:179], v155 offset:256
	ds_read_b128 v[180:183], v155 offset:288
	s_waitcnt lgkmcnt(1)
	s_nop 8
	v_pk_mul_f32 v[34:35], v[176:177], v[34:35]
	v_pk_mul_f32 v[36:37], v[36:37], v[178:179]
	ds_read_b128 v[176:179], v155 offset:320
	s_waitcnt lgkmcnt(1)
	v_pk_mul_f32 v[38:39], v[38:39], v[180:181]
	v_pk_mul_f32 v[40:41], v[40:41], v[182:183]
	s_waitcnt lgkmcnt(0)
	v_pk_mul_f32 v[42:43], v[42:43], v[176:177]
	v_pk_mul_f32 v[44:45], v[44:45], v[178:179]
	ds_read_b128 v[176:179], v155 offset:352
	s_waitcnt lgkmcnt(0)
	v_pk_mul_f32 v[46:47], v[46:47], v[176:177]
	v_pk_mul_f32 v[48:49], v[48:49], v[178:179]
	ds_read_b128 v[176:179], v163 offset:48640
	ds_read_b128 v[180:183], v163 offset:48672
	ds_read_b128 v[184:187], v174 offset:53248
	ds_read_b128 v[188:191], v174 offset:53280
	s_waitcnt lgkmcnt(1)
	v_mfma_f32_32x32x16_bf16 v[50:65], v[176:179], v[184:187], v[50:65]
	s_waitcnt lgkmcnt(0)
	v_mfma_f32_32x32x16_bf16 v[50:65], v[180:183], v[188:191], v[50:65]
	ds_read_b128 v[176:179], v163 offset:48704
	ds_read_b128 v[180:183], v174 offset:53312
	s_waitcnt lgkmcnt(0)
	v_mfma_f32_32x32x16_bf16 v[50:65], v[176:179], v[180:183], v[50:65]
	ds_read_b128 v[176:179], v163 offset:48736
	ds_read_b128 v[180:183], v174 offset:53344
	s_waitcnt lgkmcnt(0)
	v_mfma_f32_32x32x16_bf16 v[50:65], v[176:179], v[180:183], v[50:65]
	ds_read_b128 v[176:179], v155 offset:384
	ds_read_b128 v[180:183], v155 offset:416
	s_waitcnt lgkmcnt(1)
	s_nop 8
	v_pk_mul_f32 v[50:51], v[176:177], v[50:51]
	v_pk_mul_f32 v[52:53], v[52:53], v[178:179]
	ds_read_b128 v[176:179], v155 offset:448
	s_waitcnt lgkmcnt(1)
	v_pk_mul_f32 v[54:55], v[54:55], v[180:181]
	v_pk_mul_f32 v[56:57], v[56:57], v[182:183]
	s_waitcnt lgkmcnt(0)
	v_pk_mul_f32 v[58:59], v[58:59], v[176:177]
	v_pk_mul_f32 v[60:61], v[60:61], v[178:179]
	ds_read_b128 v[176:179], v155 offset:480
	s_waitcnt lgkmcnt(0)
	v_pk_mul_f32 v[62:63], v[62:63], v[176:177]
	v_pk_mul_f32 v[64:65], v[64:65], v[178:179]
	v_mfma_f32_32x32x16_bf16 v[66:81], v[98:101], v[122:125], v[66:81]
	s_barrier
	v_add_u32_e32 v98, 0x4200, v171
	s_waitcnt vmcnt(3)
	v_and_b32_e32 v177, 0xffff0000, v121
	v_and_b32_e32 v176, 0xffff0000, v120
	s_mov_b32 s42, 0x800000
	v_mfma_f32_32x32x16_bf16 v[82:97], v[102:105], v[122:125], v[82:97]
	s_nop 4
	ds_write2_b32 v171, v66, v67 offset1:132
	v_add_u32_e32 v66, 0x400, v171
	ds_write2_b32 v66, v68, v69 offset0:8 offset1:140
	v_add_u32_e32 v66, 0x4600, v171
	v_lshlrev_b32_e32 v105, 16, v119
	v_lshlrev_b32_e32 v104, 16, v118
	v_and_b32_e32 v123, 0xffff0000, v119
	ds_write2_b32 v66, v84, v85 offset0:8 offset1:140
	v_add_u32_e32 v66, 0x1000, v171
	ds_write2_b32 v66, v70, v71 offset0:32 offset1:164
	v_add_u32_e32 v66, 0x5200, v171
	ds_write2_b32 v66, v86, v87 offset0:32 offset1:164
	v_add_u32_e32 v66, 0x1400, v171
	ds_write2_b32 v66, v72, v73 offset0:40 offset1:172
	v_add_u32_e32 v66, 0x5600, v171
	ds_write2_b32 v66, v88, v89 offset0:40 offset1:172
	v_add_u32_e32 v66, 0x2000, v171
	ds_write2_b32 v66, v74, v75 offset0:64 offset1:196
	v_add_u32_e32 v66, 0x6200, v171
	ds_write2_b32 v66, v90, v91 offset0:64 offset1:196
	v_add_u32_e32 v66, 0x2400, v171
	ds_write2_b32 v66, v76, v77 offset0:72 offset1:204
	v_add_u32_e32 v66, 0x6600, v171
	ds_write2_b32 v66, v92, v93 offset0:72 offset1:204
	v_add_u32_e32 v66, 0x3000, v171
	ds_write2_b32 v66, v78, v79 offset0:96 offset1:228
	v_add_u32_e32 v66, 0x7200, v171
	ds_write2_b32 v66, v94, v95 offset0:96 offset1:228
	v_add_u32_e32 v66, 0x3400, v171
	ds_write2_b32 v66, v80, v81 offset0:104 offset1:236
	v_add_u32_e32 v66, 0x7600, v171
	ds_write2_b32 v98, v82, v83 offset1:132
	ds_write2_b32 v66, v96, v97 offset0:104 offset1:236
	s_waitcnt lgkmcnt(0)
	s_barrier
	ds_read_b128 v[92:95], v236
	ds_read_b128 v[96:99], v236 offset:16
	ds_read_b128 v[100:103], v157
	v_and_b32_e32 v122, 0xffff0000, v118
	v_lshlrev_b32_e32 v125, 16, v121
	v_lshlrev_b32_e32 v124, 16, v120
	ds_read_b128 v[118:121], v157 offset:16
	ds_read_b128 v[78:81], v157 offset:32
	ds_read_b128 v[74:77], v157 offset:48
	s_waitcnt lgkmcnt(3)
	v_pk_mul_f32 v[182:183], v[100:101], v[100:101]
	v_mov_b32_e32 v178, v100
	v_pk_mul_f32 v[180:181], v[102:103], v[102:103]
	v_add_f32_e32 v100, v182, v183
	v_add_f32_e32 v100, v100, v180
	s_waitcnt lgkmcnt(2)
	v_pk_mul_f32 v[186:187], v[118:119], v[118:119]
	v_add_f32_e32 v100, v100, v181
	v_add_f32_e32 v100, v100, v186
	v_pk_mul_f32 v[184:185], v[120:121], v[120:121]
	v_add_f32_e32 v100, v100, v187
	v_add_f32_e32 v100, v100, v184
	s_waitcnt lgkmcnt(1)
	v_pk_mul_f32 v[190:191], v[78:79], v[78:79]
	v_add_f32_e32 v100, v100, v185
	v_add_f32_e32 v100, v100, v190
	v_pk_mul_f32 v[188:189], v[80:81], v[80:81]
	v_add_f32_e32 v100, v100, v191
	ds_read_b128 v[86:89], v157 offset:64
	ds_read_b128 v[82:85], v157 offset:80
	v_add_f32_e32 v100, v100, v188
	s_waitcnt lgkmcnt(2)
	v_pk_mul_f32 v[194:195], v[74:75], v[74:75]
	v_add_f32_e32 v100, v100, v189
	v_add_f32_e32 v100, v100, v194
	v_pk_mul_f32 v[192:193], v[76:77], v[76:77]
	v_add_f32_e32 v100, v100, v195
	v_add_f32_e32 v100, v100, v192
	s_waitcnt lgkmcnt(1)
	v_pk_mul_f32 v[198:199], v[86:87], v[86:87]
	v_add_f32_e32 v100, v100, v193
	v_add_f32_e32 v100, v100, v198
	v_pk_mul_f32 v[196:197], v[88:89], v[88:89]
	v_add_f32_e32 v100, v100, v199
	ds_read_b128 v[66:69], v157 offset:96
	ds_read_b128 v[70:73], v157 offset:112
	v_add_f32_e32 v100, v100, v196
	s_waitcnt lgkmcnt(2)
	v_pk_mul_f32 v[202:203], v[82:83], v[82:83]
	v_add_f32_e32 v100, v100, v197
	v_add_f32_e32 v100, v100, v202
	v_pk_mul_f32 v[200:201], v[84:85], v[84:85]
	v_add_f32_e32 v100, v100, v203
	v_add_f32_e32 v100, v100, v200
	s_waitcnt lgkmcnt(1)
	v_pk_mul_f32 v[204:205], v[66:67], v[66:67]
	v_add_f32_e32 v100, v100, v201
	v_add_f32_e32 v100, v100, v204
	v_pk_mul_f32 v[206:207], v[68:69], v[68:69]
	v_add_f32_e32 v100, v100, v205
	v_add_f32_e32 v100, v100, v206
	s_waitcnt lgkmcnt(0)
	v_pk_mul_f32 v[208:209], v[70:71], v[70:71]
	v_add_f32_e32 v100, v100, v207
	v_add_f32_e32 v100, v100, v208
	v_pk_mul_f32 v[210:211], v[72:73], v[72:73]
	v_add_f32_e32 v100, v100, v209
	v_add_f32_e32 v100, v100, v210
	v_add_f32_e32 v175, v100, v211
	ds_bpermute_b32 v180, v172, v175
	v_mov_b32_e32 v179, v102
	v_mov_b32_e32 v102, v101
	v_mov_b32_e32 v181, v120
	v_mov_b32_e32 v120, v119
	v_lshl_add_u64 v[90:91], s[82:83], 0, v[144:145]
	s_add_i32 s44, s44, -1
	v_lshl_add_u64 v[138:139], v[138:139], 0, s[62:63]
	v_lshl_add_u64 v[140:141], v[140:141], 0, s[90:91]
	v_lshl_add_u64 v[142:143], v[142:143], 0, s[62:63]
	s_cmp_eq_u32 s44, 0
	v_lshl_add_u64 v[144:145], v[144:145], 0, s[90:91]
	s_waitcnt vmcnt(1)
	v_mov_b32_e32 v100, v92
	s_waitcnt lgkmcnt(0)
	v_add_f32_e32 v92, v175, v180
	ds_bpermute_b32 v175, v173, v92
	v_mov_b32_e32 v101, v94
	v_mov_b32_e32 v94, v93
	v_mov_b32_e32 v180, v118
	s_waitcnt vmcnt(0)
	v_mov_b32_e32 v118, v96
	s_waitcnt lgkmcnt(0)
	v_add_f32_e32 v92, v92, v175
	v_fmamk_f32 v92, v92, 0x3c000000, v164
	v_mul_f32_e32 v93, 0x4b800000, v92
	v_cmp_gt_f32_e32 vcc, s42, v92
	v_mov_b32_e32 v119, v98
	v_mov_b32_e32 v98, v97
	v_cndmask_b32_e32 v92, v92, v93, vcc
	v_rsq_f32_e32 v92, v92
	s_nop 0
	v_mul_f32_e32 v93, 0x45800000, v92
	v_cndmask_b32_e32 v92, v92, v93, vcc
	v_pk_mul_f32 v[96:97], v[178:179], v[92:93] op_sel_hi:[1,0]
	s_nop 0
	v_pk_mul_f32 v[96:97], v[100:101], v[96:97]
	v_pk_mul_f32 v[100:101], v[102:103], v[92:93] op_sel_hi:[1,0]
	v_pk_mul_f32 v[96:97], v[96:97], v[104:105]
	v_pk_mul_f32 v[94:95], v[94:95], v[100:101]
	v_and_b32_sdwa v100, v96, v169 dst_sel:DWORD dst_unused:UNUSED_PAD src0_sel:WORD_1 src1_sel:DWORD
	v_pk_mul_f32 v[94:95], v[94:95], v[122:123]
	v_add3_u32 v96, v96, v100, s33
	v_and_b32_sdwa v100, v94, v169 dst_sel:DWORD dst_unused:UNUSED_PAD src0_sel:WORD_1 src1_sel:DWORD
	v_and_b32_sdwa v93, v97, v169 dst_sel:DWORD dst_unused:UNUSED_PAD src0_sel:WORD_1 src1_sel:DWORD
	v_add3_u32 v94, v94, v100, s33
	v_add3_u32 v93, v97, v93, s33
	v_and_b32_sdwa v97, v95, v169 dst_sel:DWORD dst_unused:UNUSED_PAD src0_sel:WORD_1 src1_sel:DWORD
	v_and_b32_e32 v94, 0xffff0000, v94
	v_add3_u32 v95, v95, v97, s33
	v_or_b32_sdwa v94, v94, v96 dst_sel:DWORD dst_unused:UNUSED_PAD src0_sel:DWORD src1_sel:WORD_1
	v_pk_mul_f32 v[96:97], v[180:181], v[92:93] op_sel_hi:[1,0]
	v_pk_mul_f32 v[100:101], v[120:121], v[92:93] op_sel_hi:[1,0]
	v_pk_mul_f32 v[96:97], v[118:119], v[96:97]
	v_and_b32_e32 v95, 0xffff0000, v95
	v_pk_mul_f32 v[96:97], v[96:97], v[124:125]
	v_pk_mul_f32 v[98:99], v[98:99], v[100:101]
	v_or_b32_sdwa v95, v95, v93 dst_sel:DWORD dst_unused:UNUSED_PAD src0_sel:DWORD src1_sel:WORD_1
	v_pk_mul_f32 v[98:99], v[98:99], v[176:177]
	v_and_b32_sdwa v93, v97, v169 dst_sel:DWORD dst_unused:UNUSED_PAD src0_sel:WORD_1 src1_sel:DWORD
	v_and_b32_sdwa v100, v96, v169 dst_sel:DWORD dst_unused:UNUSED_PAD src0_sel:WORD_1 src1_sel:DWORD
	v_add3_u32 v96, v96, v100, s33
	v_add3_u32 v93, v97, v93, s33
	v_and_b32_sdwa v97, v99, v169 dst_sel:DWORD dst_unused:UNUSED_PAD src0_sel:WORD_1 src1_sel:DWORD
	v_and_b32_sdwa v100, v98, v169 dst_sel:DWORD dst_unused:UNUSED_PAD src0_sel:WORD_1 src1_sel:DWORD
	v_add3_u32 v97, v99, v97, s33
	v_add3_u32 v98, v98, v100, s33
	v_and_b32_e32 v97, 0xffff0000, v97
	v_and_b32_e32 v98, 0xffff0000, v98
	v_or_b32_sdwa v97, v97, v93 dst_sel:DWORD dst_unused:UNUSED_PAD src0_sel:DWORD src1_sel:WORD_1
	v_or_b32_sdwa v96, v98, v96 dst_sel:DWORD dst_unused:UNUSED_PAD src0_sel:DWORD src1_sel:WORD_1
	global_store_dwordx4 v[90:91], v[94:97], off offset:-32
	s_nop 1
	ds_read_b128 v[94:97], v236 offset:32
	s_nop 0
	ds_read_b128 v[98:101], v236 offset:48
	v_mov_b32_e32 v118, v78
	v_mov_b32_e32 v119, v80
	v_mov_b32_e32 v80, v79
	v_mov_b32_e32 v78, v74
	v_mov_b32_e32 v79, v76
	v_mov_b32_e32 v76, v75
	v_pk_mul_f32 v[74:75], v[118:119], v[92:93] op_sel_hi:[1,0]
	v_lshlrev_b32_e32 v103, 16, v115
	v_lshlrev_b32_e32 v102, 16, v114
	v_pk_mul_f32 v[80:81], v[80:81], v[92:93] op_sel_hi:[1,0]
	v_and_b32_e32 v105, 0xffff0000, v115
	v_and_b32_e32 v104, 0xffff0000, v114
	v_lshlrev_b32_e32 v115, 16, v117
	v_lshlrev_b32_e32 v114, 16, v116
	v_and_b32_e32 v117, 0xffff0000, v117
	v_and_b32_e32 v116, 0xffff0000, v116
	s_waitcnt lgkmcnt(1)
	v_mov_b32_e32 v118, v94
	v_mov_b32_e32 v119, v96
	v_pk_mul_f32 v[74:75], v[74:75], v[118:119]
	v_mov_b32_e32 v96, v95
	v_pk_mul_f32 v[74:75], v[74:75], v[102:103]
	v_pk_mul_f32 v[80:81], v[80:81], v[96:97]
	v_and_b32_sdwa v93, v75, v169 dst_sel:DWORD dst_unused:UNUSED_PAD src0_sel:WORD_1 src1_sel:DWORD
	v_pk_mul_f32 v[80:81], v[80:81], v[104:105]
	v_and_b32_sdwa v94, v74, v169 dst_sel:DWORD dst_unused:UNUSED_PAD src0_sel:WORD_1 src1_sel:DWORD
	v_add3_u32 v74, v74, v94, s33
	v_add3_u32 v75, v75, v93, s33
	v_and_b32_sdwa v93, v81, v169 dst_sel:DWORD dst_unused:UNUSED_PAD src0_sel:WORD_1 src1_sel:DWORD
	v_and_b32_sdwa v94, v80, v169 dst_sel:DWORD dst_unused:UNUSED_PAD src0_sel:WORD_1 src1_sel:DWORD
	v_add3_u32 v81, v81, v93, s33
	v_add3_u32 v80, v80, v94, s33
	v_and_b32_e32 v81, 0xffff0000, v81
	v_and_b32_e32 v80, 0xffff0000, v80
	v_or_b32_sdwa v75, v81, v75 dst_sel:DWORD dst_unused:UNUSED_PAD src0_sel:DWORD src1_sel:WORD_1
	v_or_b32_sdwa v74, v80, v74 dst_sel:DWORD dst_unused:UNUSED_PAD src0_sel:DWORD src1_sel:WORD_1
	v_pk_mul_f32 v[78:79], v[78:79], v[92:93] op_sel_hi:[1,0]
	s_waitcnt lgkmcnt(0)
	v_mov_b32_e32 v80, v98
	v_mov_b32_e32 v81, v100
	v_pk_mul_f32 v[78:79], v[78:79], v[80:81]
	v_pk_mul_f32 v[76:77], v[76:77], v[92:93] op_sel_hi:[1,0]
	v_mov_b32_e32 v100, v99
	v_pk_mul_f32 v[78:79], v[78:79], v[114:115]
	v_pk_mul_f32 v[76:77], v[76:77], v[100:101]
	v_and_b32_sdwa v80, v79, v169 dst_sel:DWORD dst_unused:UNUSED_PAD src0_sel:WORD_1 src1_sel:DWORD
	v_pk_mul_f32 v[76:77], v[76:77], v[116:117]
	v_and_b32_sdwa v81, v78, v169 dst_sel:DWORD dst_unused:UNUSED_PAD src0_sel:WORD_1 src1_sel:DWORD
	v_add3_u32 v78, v78, v81, s33
	v_add3_u32 v79, v79, v80, s33
	v_and_b32_sdwa v80, v77, v169 dst_sel:DWORD dst_unused:UNUSED_PAD src0_sel:WORD_1 src1_sel:DWORD
	v_and_b32_sdwa v81, v76, v169 dst_sel:DWORD dst_unused:UNUSED_PAD src0_sel:WORD_1 src1_sel:DWORD
	v_add3_u32 v77, v77, v80, s33
	v_add3_u32 v76, v76, v81, s33
	v_and_b32_e32 v77, 0xffff0000, v77
	v_and_b32_e32 v76, 0xffff0000, v76
	v_or_b32_sdwa v77, v77, v79 dst_sel:DWORD dst_unused:UNUSED_PAD src0_sel:DWORD src1_sel:WORD_1
	v_or_b32_sdwa v76, v76, v78 dst_sel:DWORD dst_unused:UNUSED_PAD src0_sel:DWORD src1_sel:WORD_1
	global_store_dwordx4 v[90:91], v[74:77], off offset:-16
	s_nop 1
	ds_read_b128 v[74:77], v236 offset:64
	s_nop 0
	ds_read_b128 v[78:81], v236 offset:80
	v_mov_b32_e32 v102, v86
	v_mov_b32_e32 v103, v88
	v_mov_b32_e32 v88, v87
	v_mov_b32_e32 v86, v82
	v_mov_b32_e32 v87, v84
	v_mov_b32_e32 v84, v83
	v_pk_mul_f32 v[82:83], v[102:103], v[92:93] op_sel_hi:[1,0]
	v_pk_mul_f32 v[88:89], v[88:89], v[92:93] op_sel_hi:[1,0]
	v_lshlrev_b32_e32 v95, 16, v111
	v_lshlrev_b32_e32 v94, 16, v110
	v_and_b32_e32 v97, 0xffff0000, v111
	v_and_b32_e32 v96, 0xffff0000, v110
	v_pk_mul_f32 v[86:87], v[86:87], v[92:93] op_sel_hi:[1,0]
	v_lshlrev_b32_e32 v99, 16, v113
	v_lshlrev_b32_e32 v98, 16, v112
	v_pk_mul_f32 v[84:85], v[84:85], v[92:93] op_sel_hi:[1,0]
	v_and_b32_e32 v101, 0xffff0000, v113
	v_and_b32_e32 v100, 0xffff0000, v112
	s_waitcnt lgkmcnt(1)
	v_mov_b32_e32 v102, v74
	v_mov_b32_e32 v103, v76
	v_mov_b32_e32 v76, v75
	s_waitcnt lgkmcnt(0)
	v_mov_b32_e32 v74, v78
	v_mov_b32_e32 v75, v80
	v_mov_b32_e32 v80, v79
	v_pk_mul_f32 v[78:79], v[82:83], v[102:103]
	v_pk_mul_f32 v[76:77], v[88:89], v[76:77]
	v_pk_mul_f32 v[74:75], v[86:87], v[74:75]
	v_pk_mul_f32 v[78:79], v[78:79], v[94:95]
	v_pk_mul_f32 v[76:77], v[76:77], v[96:97]
	v_pk_mul_f32 v[80:81], v[84:85], v[80:81]
	v_pk_mul_f32 v[82:83], v[74:75], v[98:99]
	v_and_b32_sdwa v75, v78, v169 dst_sel:DWORD dst_unused:UNUSED_PAD src0_sel:WORD_1 src1_sel:DWORD
	v_and_b32_sdwa v84, v77, v169 dst_sel:DWORD dst_unused:UNUSED_PAD src0_sel:WORD_1 src1_sel:DWORD
	v_and_b32_sdwa v85, v76, v169 dst_sel:DWORD dst_unused:UNUSED_PAD src0_sel:WORD_1 src1_sel:DWORD
	v_and_b32_sdwa v74, v79, v169 dst_sel:DWORD dst_unused:UNUSED_PAD src0_sel:WORD_1 src1_sel:DWORD
	v_add3_u32 v78, v78, v75, s33
	v_add3_u32 v75, v77, v84, s33
	v_add3_u32 v76, v76, v85, s33
	v_pk_mul_f32 v[80:81], v[80:81], v[100:101]
	v_add3_u32 v74, v79, v74, s33
	v_and_b32_e32 v75, 0xffff0000, v75
	v_and_b32_e32 v76, 0xffff0000, v76
	v_or_b32_sdwa v75, v75, v74 dst_sel:DWORD dst_unused:UNUSED_PAD src0_sel:DWORD src1_sel:WORD_1
	v_or_b32_sdwa v74, v76, v78 dst_sel:DWORD dst_unused:UNUSED_PAD src0_sel:DWORD src1_sel:WORD_1
	v_and_b32_sdwa v78, v81, v169 dst_sel:DWORD dst_unused:UNUSED_PAD src0_sel:WORD_1 src1_sel:DWORD
	v_and_b32_sdwa v79, v80, v169 dst_sel:DWORD dst_unused:UNUSED_PAD src0_sel:WORD_1 src1_sel:DWORD
	v_and_b32_sdwa v86, v83, v169 dst_sel:DWORD dst_unused:UNUSED_PAD src0_sel:WORD_1 src1_sel:DWORD
	v_and_b32_sdwa v76, v82, v169 dst_sel:DWORD dst_unused:UNUSED_PAD src0_sel:WORD_1 src1_sel:DWORD
	v_add3_u32 v78, v81, v78, s33
	v_add3_u32 v79, v80, v79, s33
	v_add3_u32 v76, v82, v76, s33
	v_add3_u32 v77, v83, v86, s33
	v_and_b32_e32 v78, 0xffff0000, v78
	v_and_b32_e32 v79, 0xffff0000, v79
	v_or_b32_sdwa v77, v78, v77 dst_sel:DWORD dst_unused:UNUSED_PAD src0_sel:DWORD src1_sel:WORD_1
	v_or_b32_sdwa v76, v79, v76 dst_sel:DWORD dst_unused:UNUSED_PAD src0_sel:DWORD src1_sel:WORD_1
	global_store_dwordx4 v[90:91], v[74:77], off
	s_nop 1
	ds_read_b128 v[74:77], v236 offset:96
	s_nop 0
	ds_read_b128 v[78:81], v236 offset:112
	v_mov_b32_e32 v94, v66
	v_mov_b32_e32 v95, v68
	v_mov_b32_e32 v66, v67
	v_mov_b32_e32 v67, v69
	v_mov_b32_e32 v68, v70
	v_mov_b32_e32 v69, v72
	v_mov_b32_e32 v70, v71
	v_mov_b32_e32 v71, v73
	v_pk_mul_f32 v[72:73], v[94:95], v[92:93] op_sel_hi:[1,0]
	v_pk_mul_f32 v[66:67], v[66:67], v[92:93] op_sel_hi:[1,0]
	v_pk_mul_f32 v[68:69], v[68:69], v[92:93] op_sel_hi:[1,0]
	v_pk_mul_f32 v[70:71], v[70:71], v[92:93] op_sel_hi:[1,0]
	v_and_b32_e32 v85, 0xffff0000, v107
	v_and_b32_e32 v84, 0xffff0000, v106
	v_and_b32_e32 v89, 0xffff0000, v109
	v_and_b32_e32 v88, 0xffff0000, v108
	v_lshlrev_b32_e32 v83, 16, v107
	v_lshlrev_b32_e32 v82, 16, v106
	v_lshlrev_b32_e32 v87, 16, v109
	v_lshlrev_b32_e32 v86, 16, v108
	s_waitcnt lgkmcnt(1)
	v_mov_b32_e32 v93, v76
	v_mov_b32_e32 v76, v75
	s_waitcnt lgkmcnt(0)
	v_mov_b32_e32 v75, v80
	v_mov_b32_e32 v80, v79
	v_mov_b32_e32 v92, v74
	v_mov_b32_e32 v74, v78
	v_pk_mul_f32 v[66:67], v[66:67], v[76:77]
	v_pk_mul_f32 v[70:71], v[70:71], v[80:81]
	v_pk_mul_f32 v[72:73], v[72:73], v[92:93]
	v_pk_mul_f32 v[68:69], v[68:69], v[74:75]
	v_pk_mul_f32 v[66:67], v[66:67], v[84:85]
	v_pk_mul_f32 v[70:71], v[70:71], v[88:89]
	v_pk_mul_f32 v[72:73], v[72:73], v[82:83]
	v_pk_mul_f32 v[68:69], v[68:69], v[86:87]
	v_and_b32_sdwa v76, v67, v169 dst_sel:DWORD dst_unused:UNUSED_PAD src0_sel:WORD_1 src1_sel:DWORD
	v_and_b32_sdwa v77, v66, v169 dst_sel:DWORD dst_unused:UNUSED_PAD src0_sel:WORD_1 src1_sel:DWORD
	v_and_b32_sdwa v80, v71, v169 dst_sel:DWORD dst_unused:UNUSED_PAD src0_sel:WORD_1 src1_sel:DWORD
	v_and_b32_sdwa v81, v70, v169 dst_sel:DWORD dst_unused:UNUSED_PAD src0_sel:WORD_1 src1_sel:DWORD
	v_and_b32_sdwa v74, v73, v169 dst_sel:DWORD dst_unused:UNUSED_PAD src0_sel:WORD_1 src1_sel:DWORD
	v_and_b32_sdwa v75, v72, v169 dst_sel:DWORD dst_unused:UNUSED_PAD src0_sel:WORD_1 src1_sel:DWORD
	v_and_b32_sdwa v78, v69, v169 dst_sel:DWORD dst_unused:UNUSED_PAD src0_sel:WORD_1 src1_sel:DWORD
	v_and_b32_sdwa v79, v68, v169 dst_sel:DWORD dst_unused:UNUSED_PAD src0_sel:WORD_1 src1_sel:DWORD
	v_add3_u32 v67, v67, v76, s33
	v_add3_u32 v66, v66, v77, s33
	v_add3_u32 v71, v71, v80, s33
	v_add3_u32 v70, v70, v81, s33
	v_add3_u32 v72, v72, v75, s33
	v_add3_u32 v73, v73, v74, s33
	v_add3_u32 v68, v68, v79, s33
	v_add3_u32 v69, v69, v78, s33
	v_and_b32_e32 v67, 0xffff0000, v67
	v_and_b32_e32 v66, 0xffff0000, v66
	v_and_b32_e32 v71, 0xffff0000, v71
	v_and_b32_e32 v70, 0xffff0000, v70
	v_or_b32_sdwa v67, v67, v73 dst_sel:DWORD dst_unused:UNUSED_PAD src0_sel:DWORD src1_sel:WORD_1
	v_or_b32_sdwa v66, v66, v72 dst_sel:DWORD dst_unused:UNUSED_PAD src0_sel:DWORD src1_sel:WORD_1
	v_or_b32_sdwa v69, v71, v69 dst_sel:DWORD dst_unused:UNUSED_PAD src0_sel:DWORD src1_sel:WORD_1
	v_or_b32_sdwa v68, v70, v68 dst_sel:DWORD dst_unused:UNUSED_PAD src0_sel:DWORD src1_sel:WORD_1
	global_store_dwordx4 v[90:91], v[66:69], off offset:16
	s_cbranch_scc1 .LBB0_167
